# phase 13 PLE part hand-written with 256x128 tiles (K=256 product parked as bf16 in a per-block slab, then K=2048 product + epilogue), per-block cyclic K start
# baseline (speedup 1.0000x reference)
.LBB0_967:
	s_cmp_lg_u32 s96, 0x200
	s_cbranch_scc1 .Lple_skip
	s_mov_b64 exec, -1
	v_lshrrev_b32_e32 v238, 3, v199
	v_lshrrev_b32_e32 v239, 4, v199
	v_xor_b32_e32 v239, v239, v199
	v_and_b32_e32 v239, 7, v239
	v_lshlrev_b32_e32 v239, 4, v239
	v_lshl_add_u32 v192, v238, 9, v239
	v_add_u32_e32 v193, 0x4000, v192
	v_add_u32_e32 v194, 0x8000, v192
	v_add_u32_e32 v195, 0xc000, v192
	v_lshl_add_u32 v244, v238, 12, v239
	v_add_u32_e32 v245, 0x20000, v244
	v_add_u32_e32 v246, 0x40000, v244
	v_add_u32_e32 v247, 0x60000, v244
	v_and_b32_e32 v238, 15, v199
	v_bfe_u32 v239, v199, 4, 2
	v_lshrrev_b32_e32 v240, 1, v238
	v_lshlrev_b32_e32 v202, 3, v239
	v_xor_b32_e32 v239, v239, v240
	v_lshlrev_b32_e32 v239, 4, v239
	v_xor_b32_e32 v240, 64, v239
	v_lshrrev_b32_e32 v201, 7, v199
	v_lshl_add_u32 v201, v201, 7, v238
	v_lshlrev_b32_e32 v196, 7, v201
	v_bfe_u32 v198, v199, 6, 1
	v_lshl_add_u32 v202, v198, 7, v202
	v_lshl_add_u32 v198, v198, 6, v238
	v_lshlrev_b32_e32 v198, 7, v198
	v_add_u32_e32 v198, 0x8000, v198
	v_add_u32_e32 v197, v196, v240
	v_add_u32_e32 v241, v198, v240
	v_add_u32_e32 v196, v196, v239
	v_add_u32_e32 v198, v198, v239
	v_lshlrev_b32_e32 v238, 1, v202
	v_lshl_add_u32 v203, v201, 13, v238
	v_lshl_add_u32 v236, v201, 8, v202
	v_lshrrev_b32_e32 v238, 6, v199
	v_lshlrev_b32_e32 v238, 10, v238
	s_nop 0
	v_readfirstlane_b32 s26, v238
	s_mov_b32 s36, 0xbfb8aa3b
	s_mov_b32 s37, 0x3f9837f0
	v_readlane_b32 s29, v242, 45
	s_lshl_b32 s28, s29, 16
	s_add_u32 s34, s94, s28
	s_addc_u32 s35, s95, 0
.Lple_tile:
	s_and_b32 s28, s29, 63
	s_lshl_b32 s28, s28, 17
	s_add_u32 s40, s94, s28
	s_addc_u32 s41, s95, 0
	s_add_u32 s40, s40, 0x1d3a0000
	s_addc_u32 s41, s41, 0
	s_add_u32 s42, s40, 0x10000
	s_addc_u32 s43, s41, 0
	s_lshr_b32 s28, s29, 6
	s_lshl_b32 s28, s28, 16
	s_add_u32 s44, s94, s28
	s_addc_u32 s45, s95, 0
	s_add_u32 s44, s44, 0x1d200000
	s_addc_u32 s45, s45, 0
	s_mov_b32 s46, 0x180
	v_readlane_b32 s39, v242, 45
	s_lshl_b32 s39, s39, 7
	s_and_b32 s39, s39, s46
	s_add_u32 s20, s40, s39
	s_addc_u32 s21, s41, 0
	s_add_u32 s22, s42, s39
	s_addc_u32 s23, s43, 0
	s_add_u32 s24, s44, s39
	s_addc_u32 s25, s45, 0
	s_barrier
	s_add_u32 m0, s26, 0x0
	s_nop 0
	global_load_lds_dwordx4 v192, s[20:21]
	s_add_u32 m0, s26, 0x1000
	s_nop 0
	global_load_lds_dwordx4 v193, s[20:21]
	s_add_u32 m0, s26, 0x2000
	s_nop 0
	global_load_lds_dwordx4 v194, s[20:21]
	s_add_u32 m0, s26, 0x3000
	s_nop 0
	global_load_lds_dwordx4 v195, s[20:21]
	s_add_u32 m0, s26, 0x4000
	s_nop 0
	global_load_lds_dwordx4 v192, s[22:23]
	s_add_u32 m0, s26, 0x5000
	s_nop 0
	global_load_lds_dwordx4 v193, s[22:23]
	s_add_u32 m0, s26, 0x6000
	s_nop 0
	global_load_lds_dwordx4 v194, s[22:23]
	s_add_u32 m0, s26, 0x7000
	s_nop 0
	global_load_lds_dwordx4 v195, s[22:23]
	s_add_u32 m0, s26, 0x8000
	s_nop 0
	global_load_lds_dwordx4 v192, s[24:25]
	s_add_u32 m0, s26, 0x9000
	s_nop 0
	global_load_lds_dwordx4 v193, s[24:25]
	s_add_u32 m0, s26, 0xa000
	s_nop 0
	global_load_lds_dwordx4 v194, s[24:25]
	s_add_u32 m0, s26, 0xb000
	s_nop 0
	global_load_lds_dwordx4 v195, s[24:25]
	s_add_u32 s39, s39, 0x80
	s_and_b32 s39, s39, s46
	s_add_u32 s20, s40, s39
	s_addc_u32 s21, s41, 0
	s_add_u32 s22, s42, s39
	s_addc_u32 s23, s43, 0
	s_add_u32 s24, s44, s39
	s_addc_u32 s25, s45, 0
	v_mov_b32_e32 v0, 0
	v_mov_b32_e32 v1, 0
	v_mov_b32_e32 v2, 0
	v_mov_b32_e32 v3, 0
	v_mov_b32_e32 v4, 0
	v_mov_b32_e32 v5, 0
	v_mov_b32_e32 v6, 0
	v_mov_b32_e32 v7, 0
	v_mov_b32_e32 v8, 0
	v_mov_b32_e32 v9, 0
	v_mov_b32_e32 v10, 0
	v_mov_b32_e32 v11, 0
	v_mov_b32_e32 v12, 0
	v_mov_b32_e32 v13, 0
	v_mov_b32_e32 v14, 0
	v_mov_b32_e32 v15, 0
	v_mov_b32_e32 v16, 0
	v_mov_b32_e32 v17, 0
	v_mov_b32_e32 v18, 0
	v_mov_b32_e32 v19, 0
	v_mov_b32_e32 v20, 0
	v_mov_b32_e32 v21, 0
	v_mov_b32_e32 v22, 0
	v_mov_b32_e32 v23, 0
	v_mov_b32_e32 v24, 0
	v_mov_b32_e32 v25, 0
	v_mov_b32_e32 v26, 0
	v_mov_b32_e32 v27, 0
	v_mov_b32_e32 v28, 0
	v_mov_b32_e32 v29, 0
	v_mov_b32_e32 v30, 0
	v_mov_b32_e32 v31, 0
	v_mov_b32_e32 v32, 0
	v_mov_b32_e32 v33, 0
	v_mov_b32_e32 v34, 0
	v_mov_b32_e32 v35, 0
	v_mov_b32_e32 v36, 0
	v_mov_b32_e32 v37, 0
	v_mov_b32_e32 v38, 0
	v_mov_b32_e32 v39, 0
	v_mov_b32_e32 v40, 0
	v_mov_b32_e32 v41, 0
	v_mov_b32_e32 v42, 0
	v_mov_b32_e32 v43, 0
	v_mov_b32_e32 v44, 0
	v_mov_b32_e32 v45, 0
	v_mov_b32_e32 v46, 0
	v_mov_b32_e32 v47, 0
	v_mov_b32_e32 v48, 0
	v_mov_b32_e32 v49, 0
	v_mov_b32_e32 v50, 0
	v_mov_b32_e32 v51, 0
	v_mov_b32_e32 v52, 0
	v_mov_b32_e32 v53, 0
	v_mov_b32_e32 v54, 0
	v_mov_b32_e32 v55, 0
	v_mov_b32_e32 v56, 0
	v_mov_b32_e32 v57, 0
	v_mov_b32_e32 v58, 0
	v_mov_b32_e32 v59, 0
	v_mov_b32_e32 v60, 0
	v_mov_b32_e32 v61, 0
	v_mov_b32_e32 v62, 0
	v_mov_b32_e32 v63, 0
	v_mov_b32_e32 v64, 0
	v_mov_b32_e32 v65, 0
	v_mov_b32_e32 v66, 0
	v_mov_b32_e32 v67, 0
	v_mov_b32_e32 v68, 0
	v_mov_b32_e32 v69, 0
	v_mov_b32_e32 v70, 0
	v_mov_b32_e32 v71, 0
	v_mov_b32_e32 v72, 0
	v_mov_b32_e32 v73, 0
	v_mov_b32_e32 v74, 0
	v_mov_b32_e32 v75, 0
	v_mov_b32_e32 v76, 0
	v_mov_b32_e32 v77, 0
	v_mov_b32_e32 v78, 0
	v_mov_b32_e32 v79, 0
	v_mov_b32_e32 v80, 0
	v_mov_b32_e32 v81, 0
	v_mov_b32_e32 v82, 0
	v_mov_b32_e32 v83, 0
	v_mov_b32_e32 v84, 0
	v_mov_b32_e32 v85, 0
	v_mov_b32_e32 v86, 0
	v_mov_b32_e32 v87, 0
	v_mov_b32_e32 v88, 0
	v_mov_b32_e32 v89, 0
	v_mov_b32_e32 v90, 0
	v_mov_b32_e32 v91, 0
	v_mov_b32_e32 v92, 0
	v_mov_b32_e32 v93, 0
	v_mov_b32_e32 v94, 0
	v_mov_b32_e32 v95, 0
	v_mov_b32_e32 v96, 0
	v_mov_b32_e32 v97, 0
	v_mov_b32_e32 v98, 0
	v_mov_b32_e32 v99, 0
	v_mov_b32_e32 v100, 0
	v_mov_b32_e32 v101, 0
	v_mov_b32_e32 v102, 0
	v_mov_b32_e32 v103, 0
	v_mov_b32_e32 v104, 0
	v_mov_b32_e32 v105, 0
	v_mov_b32_e32 v106, 0
	v_mov_b32_e32 v107, 0
	v_mov_b32_e32 v108, 0
	v_mov_b32_e32 v109, 0
	v_mov_b32_e32 v110, 0
	v_mov_b32_e32 v111, 0
	v_mov_b32_e32 v112, 0
	v_mov_b32_e32 v113, 0
	v_mov_b32_e32 v114, 0
	v_mov_b32_e32 v115, 0
	v_mov_b32_e32 v116, 0
	v_mov_b32_e32 v117, 0
	v_mov_b32_e32 v118, 0
	v_mov_b32_e32 v119, 0
	v_mov_b32_e32 v120, 0
	v_mov_b32_e32 v121, 0
	v_mov_b32_e32 v122, 0
	v_mov_b32_e32 v123, 0
	v_mov_b32_e32 v124, 0
	v_mov_b32_e32 v125, 0
	v_mov_b32_e32 v126, 0
	v_mov_b32_e32 v127, 0
	s_mov_b32 s27, 0
.Lple_ka:
	s_waitcnt vmcnt(0)
	s_barrier
	ds_read_b128 v[160:163], v198 offset:0
	ds_read_b128 v[164:167], v198 offset:2048
	ds_read_b128 v[168:171], v198 offset:4096
	ds_read_b128 v[172:175], v198 offset:6144
	ds_read_b128 v[128:131], v196 offset:0
	ds_read_b128 v[132:135], v196 offset:2048
	ds_read_b128 v[136:139], v196 offset:4096
	ds_read_b128 v[140:143], v196 offset:6144
	ds_read_b128 v[144:147], v196 offset:8192
	ds_read_b128 v[148:151], v196 offset:10240
	ds_read_b128 v[152:155], v196 offset:12288
	ds_read_b128 v[156:159], v196 offset:14336
	ds_read_b128 v[176:179], v241 offset:0
	ds_read_b128 v[180:183], v241 offset:2048
	ds_read_b128 v[184:187], v241 offset:4096
	ds_read_b128 v[188:191], v241 offset:6144
	ds_read_b128 v[204:207], v197 offset:0
	ds_read_b128 v[208:211], v197 offset:2048
	ds_read_b128 v[212:215], v197 offset:4096
	ds_read_b128 v[216:219], v197 offset:6144
	ds_read_b128 v[220:223], v197 offset:8192
	ds_read_b128 v[224:227], v197 offset:10240
	ds_read_b128 v[228:231], v197 offset:12288
	ds_read_b128 v[232:235], v197 offset:14336
	s_setprio 1
	s_waitcnt lgkmcnt(15)
	v_mfma_f32_16x16x32_bf16 v[0:3], v[160:163], v[128:131], v[0:3]
	v_mfma_f32_16x16x32_bf16 v[4:7], v[164:167], v[128:131], v[4:7]
	v_mfma_f32_16x16x32_bf16 v[8:11], v[168:171], v[128:131], v[8:11]
	v_mfma_f32_16x16x32_bf16 v[12:15], v[172:175], v[128:131], v[12:15]
	s_waitcnt lgkmcnt(15)
	v_mfma_f32_16x16x32_bf16 v[16:19], v[160:163], v[132:135], v[16:19]
	v_mfma_f32_16x16x32_bf16 v[20:23], v[164:167], v[132:135], v[20:23]
	v_mfma_f32_16x16x32_bf16 v[24:27], v[168:171], v[132:135], v[24:27]
	v_mfma_f32_16x16x32_bf16 v[28:31], v[172:175], v[132:135], v[28:31]
	s_waitcnt lgkmcnt(15)
	v_mfma_f32_16x16x32_bf16 v[32:35], v[160:163], v[136:139], v[32:35]
	v_mfma_f32_16x16x32_bf16 v[36:39], v[164:167], v[136:139], v[36:39]
	v_mfma_f32_16x16x32_bf16 v[40:43], v[168:171], v[136:139], v[40:43]
	v_mfma_f32_16x16x32_bf16 v[44:47], v[172:175], v[136:139], v[44:47]
	s_waitcnt lgkmcnt(15)
	v_mfma_f32_16x16x32_bf16 v[48:51], v[160:163], v[140:143], v[48:51]
	v_mfma_f32_16x16x32_bf16 v[52:55], v[164:167], v[140:143], v[52:55]
	v_mfma_f32_16x16x32_bf16 v[56:59], v[168:171], v[140:143], v[56:59]
	v_mfma_f32_16x16x32_bf16 v[60:63], v[172:175], v[140:143], v[60:63]
	s_waitcnt lgkmcnt(15)
	v_mfma_f32_16x16x32_bf16 v[64:67], v[160:163], v[144:147], v[64:67]
	v_mfma_f32_16x16x32_bf16 v[68:71], v[164:167], v[144:147], v[68:71]
	v_mfma_f32_16x16x32_bf16 v[72:75], v[168:171], v[144:147], v[72:75]
	v_mfma_f32_16x16x32_bf16 v[76:79], v[172:175], v[144:147], v[76:79]
	s_waitcnt lgkmcnt(14)
	v_mfma_f32_16x16x32_bf16 v[80:83], v[160:163], v[148:151], v[80:83]
	v_mfma_f32_16x16x32_bf16 v[84:87], v[164:167], v[148:151], v[84:87]
	v_mfma_f32_16x16x32_bf16 v[88:91], v[168:171], v[148:151], v[88:91]
	v_mfma_f32_16x16x32_bf16 v[92:95], v[172:175], v[148:151], v[92:95]
	s_waitcnt lgkmcnt(13)
	v_mfma_f32_16x16x32_bf16 v[96:99], v[160:163], v[152:155], v[96:99]
	v_mfma_f32_16x16x32_bf16 v[100:103], v[164:167], v[152:155], v[100:103]
	v_mfma_f32_16x16x32_bf16 v[104:107], v[168:171], v[152:155], v[104:107]
	v_mfma_f32_16x16x32_bf16 v[108:111], v[172:175], v[152:155], v[108:111]
	s_waitcnt lgkmcnt(12)
	v_mfma_f32_16x16x32_bf16 v[112:115], v[160:163], v[156:159], v[112:115]
	v_mfma_f32_16x16x32_bf16 v[116:119], v[164:167], v[156:159], v[116:119]
	v_mfma_f32_16x16x32_bf16 v[120:123], v[168:171], v[156:159], v[120:123]
	v_mfma_f32_16x16x32_bf16 v[124:127], v[172:175], v[156:159], v[124:127]
	s_setprio 0
	s_waitcnt lgkmcnt(0)
	s_barrier
	s_add_u32 m0, s26, 0x0
	s_nop 0
	global_load_lds_dwordx4 v192, s[20:21]
	s_add_u32 m0, s26, 0x1000
	s_nop 0
	global_load_lds_dwordx4 v193, s[20:21]
	s_add_u32 m0, s26, 0x2000
	s_nop 0
	global_load_lds_dwordx4 v194, s[20:21]
	s_add_u32 m0, s26, 0x3000
	s_nop 0
	global_load_lds_dwordx4 v195, s[20:21]
	s_add_u32 m0, s26, 0x4000
	s_nop 0
	global_load_lds_dwordx4 v192, s[22:23]
	s_add_u32 m0, s26, 0x5000
	s_nop 0
	global_load_lds_dwordx4 v193, s[22:23]
	s_add_u32 m0, s26, 0x6000
	s_nop 0
	global_load_lds_dwordx4 v194, s[22:23]
	s_add_u32 m0, s26, 0x7000
	s_nop 0
	global_load_lds_dwordx4 v195, s[22:23]
	s_add_u32 m0, s26, 0x8000
	s_nop 0
	global_load_lds_dwordx4 v192, s[24:25]
	s_add_u32 m0, s26, 0x9000
	s_nop 0
	global_load_lds_dwordx4 v193, s[24:25]
	s_add_u32 m0, s26, 0xa000
	s_nop 0
	global_load_lds_dwordx4 v194, s[24:25]
	s_add_u32 m0, s26, 0xb000
	s_nop 0
	global_load_lds_dwordx4 v195, s[24:25]
	s_add_u32 s39, s39, 0x80
	s_and_b32 s39, s39, s46
	s_add_u32 s20, s40, s39
	s_addc_u32 s21, s41, 0
	s_add_u32 s22, s42, s39
	s_addc_u32 s23, s43, 0
	s_add_u32 s24, s44, s39
	s_addc_u32 s25, s45, 0
	s_setprio 1
	v_mfma_f32_16x16x32_bf16 v[0:3], v[176:179], v[204:207], v[0:3]
	v_mfma_f32_16x16x32_bf16 v[4:7], v[180:183], v[204:207], v[4:7]
	v_mfma_f32_16x16x32_bf16 v[8:11], v[184:187], v[204:207], v[8:11]
	v_mfma_f32_16x16x32_bf16 v[12:15], v[188:191], v[204:207], v[12:15]
	v_mfma_f32_16x16x32_bf16 v[16:19], v[176:179], v[208:211], v[16:19]
	v_mfma_f32_16x16x32_bf16 v[20:23], v[180:183], v[208:211], v[20:23]
	v_mfma_f32_16x16x32_bf16 v[24:27], v[184:187], v[208:211], v[24:27]
	v_mfma_f32_16x16x32_bf16 v[28:31], v[188:191], v[208:211], v[28:31]
	v_mfma_f32_16x16x32_bf16 v[32:35], v[176:179], v[212:215], v[32:35]
	v_mfma_f32_16x16x32_bf16 v[36:39], v[180:183], v[212:215], v[36:39]
	v_mfma_f32_16x16x32_bf16 v[40:43], v[184:187], v[212:215], v[40:43]
	v_mfma_f32_16x16x32_bf16 v[44:47], v[188:191], v[212:215], v[44:47]
	v_mfma_f32_16x16x32_bf16 v[48:51], v[176:179], v[216:219], v[48:51]
	v_mfma_f32_16x16x32_bf16 v[52:55], v[180:183], v[216:219], v[52:55]
	v_mfma_f32_16x16x32_bf16 v[56:59], v[184:187], v[216:219], v[56:59]
	v_mfma_f32_16x16x32_bf16 v[60:63], v[188:191], v[216:219], v[60:63]
	v_mfma_f32_16x16x32_bf16 v[64:67], v[176:179], v[220:223], v[64:67]
	v_mfma_f32_16x16x32_bf16 v[68:71], v[180:183], v[220:223], v[68:71]
	v_mfma_f32_16x16x32_bf16 v[72:75], v[184:187], v[220:223], v[72:75]
	v_mfma_f32_16x16x32_bf16 v[76:79], v[188:191], v[220:223], v[76:79]
	v_mfma_f32_16x16x32_bf16 v[80:83], v[176:179], v[224:227], v[80:83]
	v_mfma_f32_16x16x32_bf16 v[84:87], v[180:183], v[224:227], v[84:87]
	v_mfma_f32_16x16x32_bf16 v[88:91], v[184:187], v[224:227], v[88:91]
	v_mfma_f32_16x16x32_bf16 v[92:95], v[188:191], v[224:227], v[92:95]
	v_mfma_f32_16x16x32_bf16 v[96:99], v[176:179], v[228:231], v[96:99]
	v_mfma_f32_16x16x32_bf16 v[100:103], v[180:183], v[228:231], v[100:103]
	v_mfma_f32_16x16x32_bf16 v[104:107], v[184:187], v[228:231], v[104:107]
	v_mfma_f32_16x16x32_bf16 v[108:111], v[188:191], v[228:231], v[108:111]
	v_mfma_f32_16x16x32_bf16 v[112:115], v[176:179], v[232:235], v[112:115]
	v_mfma_f32_16x16x32_bf16 v[116:119], v[180:183], v[232:235], v[116:119]
	v_mfma_f32_16x16x32_bf16 v[120:123], v[184:187], v[232:235], v[120:123]
	v_mfma_f32_16x16x32_bf16 v[124:127], v[188:191], v[232:235], v[124:127]
	s_setprio 0
	s_add_i32 s27, s27, 1
	s_cmp_lt_u32 s27, 3
	s_cbranch_scc1 .Lple_ka
	s_waitcnt vmcnt(0)
	s_barrier
	ds_read_b128 v[160:163], v198 offset:0
	ds_read_b128 v[164:167], v198 offset:2048
	ds_read_b128 v[168:171], v198 offset:4096
	ds_read_b128 v[172:175], v198 offset:6144
	ds_read_b128 v[128:131], v196 offset:0
	ds_read_b128 v[132:135], v196 offset:2048
	ds_read_b128 v[136:139], v196 offset:4096
	ds_read_b128 v[140:143], v196 offset:6144
	ds_read_b128 v[144:147], v196 offset:8192
	ds_read_b128 v[148:151], v196 offset:10240
	ds_read_b128 v[152:155], v196 offset:12288
	ds_read_b128 v[156:159], v196 offset:14336
	ds_read_b128 v[176:179], v241 offset:0
	ds_read_b128 v[180:183], v241 offset:2048
	ds_read_b128 v[184:187], v241 offset:4096
	ds_read_b128 v[188:191], v241 offset:6144
	ds_read_b128 v[204:207], v197 offset:0
	ds_read_b128 v[208:211], v197 offset:2048
	ds_read_b128 v[212:215], v197 offset:4096
	ds_read_b128 v[216:219], v197 offset:6144
	ds_read_b128 v[220:223], v197 offset:8192
	ds_read_b128 v[224:227], v197 offset:10240
	ds_read_b128 v[228:231], v197 offset:12288
	ds_read_b128 v[232:235], v197 offset:14336
	s_setprio 1
	s_waitcnt lgkmcnt(15)
	v_mfma_f32_16x16x32_bf16 v[0:3], v[160:163], v[128:131], v[0:3]
	v_mfma_f32_16x16x32_bf16 v[4:7], v[164:167], v[128:131], v[4:7]
	v_mfma_f32_16x16x32_bf16 v[8:11], v[168:171], v[128:131], v[8:11]
	v_mfma_f32_16x16x32_bf16 v[12:15], v[172:175], v[128:131], v[12:15]
	s_waitcnt lgkmcnt(15)
	v_mfma_f32_16x16x32_bf16 v[16:19], v[160:163], v[132:135], v[16:19]
	v_mfma_f32_16x16x32_bf16 v[20:23], v[164:167], v[132:135], v[20:23]
	v_mfma_f32_16x16x32_bf16 v[24:27], v[168:171], v[132:135], v[24:27]
	v_mfma_f32_16x16x32_bf16 v[28:31], v[172:175], v[132:135], v[28:31]
	s_waitcnt lgkmcnt(15)
	v_mfma_f32_16x16x32_bf16 v[32:35], v[160:163], v[136:139], v[32:35]
	v_mfma_f32_16x16x32_bf16 v[36:39], v[164:167], v[136:139], v[36:39]
	v_mfma_f32_16x16x32_bf16 v[40:43], v[168:171], v[136:139], v[40:43]
	v_mfma_f32_16x16x32_bf16 v[44:47], v[172:175], v[136:139], v[44:47]
	s_waitcnt lgkmcnt(15)
	v_mfma_f32_16x16x32_bf16 v[48:51], v[160:163], v[140:143], v[48:51]
	v_mfma_f32_16x16x32_bf16 v[52:55], v[164:167], v[140:143], v[52:55]
	v_mfma_f32_16x16x32_bf16 v[56:59], v[168:171], v[140:143], v[56:59]
	v_mfma_f32_16x16x32_bf16 v[60:63], v[172:175], v[140:143], v[60:63]
	s_waitcnt lgkmcnt(15)
	v_mfma_f32_16x16x32_bf16 v[64:67], v[160:163], v[144:147], v[64:67]
	v_mfma_f32_16x16x32_bf16 v[68:71], v[164:167], v[144:147], v[68:71]
	v_mfma_f32_16x16x32_bf16 v[72:75], v[168:171], v[144:147], v[72:75]
	v_mfma_f32_16x16x32_bf16 v[76:79], v[172:175], v[144:147], v[76:79]
	s_waitcnt lgkmcnt(14)
	v_mfma_f32_16x16x32_bf16 v[80:83], v[160:163], v[148:151], v[80:83]
	v_mfma_f32_16x16x32_bf16 v[84:87], v[164:167], v[148:151], v[84:87]
	v_mfma_f32_16x16x32_bf16 v[88:91], v[168:171], v[148:151], v[88:91]
	v_mfma_f32_16x16x32_bf16 v[92:95], v[172:175], v[148:151], v[92:95]
	s_waitcnt lgkmcnt(13)
	v_mfma_f32_16x16x32_bf16 v[96:99], v[160:163], v[152:155], v[96:99]
	v_mfma_f32_16x16x32_bf16 v[100:103], v[164:167], v[152:155], v[100:103]
	v_mfma_f32_16x16x32_bf16 v[104:107], v[168:171], v[152:155], v[104:107]
	v_mfma_f32_16x16x32_bf16 v[108:111], v[172:175], v[152:155], v[108:111]
	s_waitcnt lgkmcnt(12)
	v_mfma_f32_16x16x32_bf16 v[112:115], v[160:163], v[156:159], v[112:115]
	v_mfma_f32_16x16x32_bf16 v[116:119], v[164:167], v[156:159], v[116:119]
	v_mfma_f32_16x16x32_bf16 v[120:123], v[168:171], v[156:159], v[120:123]
	v_mfma_f32_16x16x32_bf16 v[124:127], v[172:175], v[156:159], v[124:127]
	s_setprio 0
	s_waitcnt lgkmcnt(0)
	s_setprio 1
	v_mfma_f32_16x16x32_bf16 v[0:3], v[176:179], v[204:207], v[0:3]
	v_mfma_f32_16x16x32_bf16 v[4:7], v[180:183], v[204:207], v[4:7]
	v_mfma_f32_16x16x32_bf16 v[8:11], v[184:187], v[204:207], v[8:11]
	v_mfma_f32_16x16x32_bf16 v[12:15], v[188:191], v[204:207], v[12:15]
	v_mfma_f32_16x16x32_bf16 v[16:19], v[176:179], v[208:211], v[16:19]
	v_mfma_f32_16x16x32_bf16 v[20:23], v[180:183], v[208:211], v[20:23]
	v_mfma_f32_16x16x32_bf16 v[24:27], v[184:187], v[208:211], v[24:27]
	v_mfma_f32_16x16x32_bf16 v[28:31], v[188:191], v[208:211], v[28:31]
	v_mfma_f32_16x16x32_bf16 v[32:35], v[176:179], v[212:215], v[32:35]
	v_mfma_f32_16x16x32_bf16 v[36:39], v[180:183], v[212:215], v[36:39]
	v_mfma_f32_16x16x32_bf16 v[40:43], v[184:187], v[212:215], v[40:43]
	v_mfma_f32_16x16x32_bf16 v[44:47], v[188:191], v[212:215], v[44:47]
	v_mfma_f32_16x16x32_bf16 v[48:51], v[176:179], v[216:219], v[48:51]
	v_mfma_f32_16x16x32_bf16 v[52:55], v[180:183], v[216:219], v[52:55]
	v_mfma_f32_16x16x32_bf16 v[56:59], v[184:187], v[216:219], v[56:59]
	v_mfma_f32_16x16x32_bf16 v[60:63], v[188:191], v[216:219], v[60:63]
	v_mfma_f32_16x16x32_bf16 v[64:67], v[176:179], v[220:223], v[64:67]
	v_mfma_f32_16x16x32_bf16 v[68:71], v[180:183], v[220:223], v[68:71]
	v_mfma_f32_16x16x32_bf16 v[72:75], v[184:187], v[220:223], v[72:75]
	v_mfma_f32_16x16x32_bf16 v[76:79], v[188:191], v[220:223], v[76:79]
	v_mfma_f32_16x16x32_bf16 v[80:83], v[176:179], v[224:227], v[80:83]
	v_mfma_f32_16x16x32_bf16 v[84:87], v[180:183], v[224:227], v[84:87]
	v_mfma_f32_16x16x32_bf16 v[88:91], v[184:187], v[224:227], v[88:91]
	v_mfma_f32_16x16x32_bf16 v[92:95], v[188:191], v[224:227], v[92:95]
	v_mfma_f32_16x16x32_bf16 v[96:99], v[176:179], v[228:231], v[96:99]
	v_mfma_f32_16x16x32_bf16 v[100:103], v[180:183], v[228:231], v[100:103]
	v_mfma_f32_16x16x32_bf16 v[104:107], v[184:187], v[228:231], v[104:107]
	v_mfma_f32_16x16x32_bf16 v[108:111], v[188:191], v[228:231], v[108:111]
	v_mfma_f32_16x16x32_bf16 v[112:115], v[176:179], v[232:235], v[112:115]
	v_mfma_f32_16x16x32_bf16 v[116:119], v[180:183], v[232:235], v[116:119]
	v_mfma_f32_16x16x32_bf16 v[120:123], v[184:187], v[232:235], v[120:123]
	v_mfma_f32_16x16x32_bf16 v[124:127], v[188:191], v[232:235], v[124:127]
	s_setprio 0
	s_nop 7
	v_cvt_pk_bf16_f32 v220, v0, v1
	v_cvt_pk_bf16_f32 v221, v2, v3
	v_cvt_pk_bf16_f32 v222, v4, v5
	v_cvt_pk_bf16_f32 v223, v6, v7
	v_cvt_pk_bf16_f32 v224, v8, v9
	v_cvt_pk_bf16_f32 v225, v10, v11
	v_cvt_pk_bf16_f32 v226, v12, v13
	v_cvt_pk_bf16_f32 v227, v14, v15
	global_store_dwordx2 v236, v[220:221], s[34:35] offset:0
	global_store_dwordx2 v236, v[222:223], s[34:35] offset:32
	global_store_dwordx2 v236, v[224:225], s[34:35] offset:64
	global_store_dwordx2 v236, v[226:227], s[34:35] offset:96
	s_add_u32 s34, s34, 0x1000
	s_addc_u32 s35, s35, 0
	v_cvt_pk_bf16_f32 v220, v16, v17
	v_cvt_pk_bf16_f32 v221, v18, v19
	v_cvt_pk_bf16_f32 v222, v20, v21
	v_cvt_pk_bf16_f32 v223, v22, v23
	v_cvt_pk_bf16_f32 v224, v24, v25
	v_cvt_pk_bf16_f32 v225, v26, v27
	v_cvt_pk_bf16_f32 v226, v28, v29
	v_cvt_pk_bf16_f32 v227, v30, v31
	global_store_dwordx2 v236, v[220:221], s[34:35] offset:0
	global_store_dwordx2 v236, v[222:223], s[34:35] offset:32
	global_store_dwordx2 v236, v[224:225], s[34:35] offset:64
	global_store_dwordx2 v236, v[226:227], s[34:35] offset:96
	s_add_u32 s34, s34, 0x1000
	s_addc_u32 s35, s35, 0
	v_cvt_pk_bf16_f32 v220, v32, v33
	v_cvt_pk_bf16_f32 v221, v34, v35
	v_cvt_pk_bf16_f32 v222, v36, v37
	v_cvt_pk_bf16_f32 v223, v38, v39
	v_cvt_pk_bf16_f32 v224, v40, v41
	v_cvt_pk_bf16_f32 v225, v42, v43
	v_cvt_pk_bf16_f32 v226, v44, v45
	v_cvt_pk_bf16_f32 v227, v46, v47
	global_store_dwordx2 v236, v[220:221], s[34:35] offset:0
	global_store_dwordx2 v236, v[222:223], s[34:35] offset:32
	global_store_dwordx2 v236, v[224:225], s[34:35] offset:64
	global_store_dwordx2 v236, v[226:227], s[34:35] offset:96
	s_add_u32 s34, s34, 0x1000
	s_addc_u32 s35, s35, 0
	v_cvt_pk_bf16_f32 v220, v48, v49
	v_cvt_pk_bf16_f32 v221, v50, v51
	v_cvt_pk_bf16_f32 v222, v52, v53
	v_cvt_pk_bf16_f32 v223, v54, v55
	v_cvt_pk_bf16_f32 v224, v56, v57
	v_cvt_pk_bf16_f32 v225, v58, v59
	v_cvt_pk_bf16_f32 v226, v60, v61
	v_cvt_pk_bf16_f32 v227, v62, v63
	global_store_dwordx2 v236, v[220:221], s[34:35] offset:0
	global_store_dwordx2 v236, v[222:223], s[34:35] offset:32
	global_store_dwordx2 v236, v[224:225], s[34:35] offset:64
	global_store_dwordx2 v236, v[226:227], s[34:35] offset:96
	s_add_u32 s34, s34, 0x1000
	s_addc_u32 s35, s35, 0
	v_cvt_pk_bf16_f32 v220, v64, v65
	v_cvt_pk_bf16_f32 v221, v66, v67
	v_cvt_pk_bf16_f32 v222, v68, v69
	v_cvt_pk_bf16_f32 v223, v70, v71
	v_cvt_pk_bf16_f32 v224, v72, v73
	v_cvt_pk_bf16_f32 v225, v74, v75
	v_cvt_pk_bf16_f32 v226, v76, v77
	v_cvt_pk_bf16_f32 v227, v78, v79
	global_store_dwordx2 v236, v[220:221], s[34:35] offset:0
	global_store_dwordx2 v236, v[222:223], s[34:35] offset:32
	global_store_dwordx2 v236, v[224:225], s[34:35] offset:64
	global_store_dwordx2 v236, v[226:227], s[34:35] offset:96
	s_add_u32 s34, s34, 0x1000
	s_addc_u32 s35, s35, 0
	v_cvt_pk_bf16_f32 v220, v80, v81
	v_cvt_pk_bf16_f32 v221, v82, v83
	v_cvt_pk_bf16_f32 v222, v84, v85
	v_cvt_pk_bf16_f32 v223, v86, v87
	v_cvt_pk_bf16_f32 v224, v88, v89
	v_cvt_pk_bf16_f32 v225, v90, v91
	v_cvt_pk_bf16_f32 v226, v92, v93
	v_cvt_pk_bf16_f32 v227, v94, v95
	global_store_dwordx2 v236, v[220:221], s[34:35] offset:0
	global_store_dwordx2 v236, v[222:223], s[34:35] offset:32
	global_store_dwordx2 v236, v[224:225], s[34:35] offset:64
	global_store_dwordx2 v236, v[226:227], s[34:35] offset:96
	s_add_u32 s34, s34, 0x1000
	s_addc_u32 s35, s35, 0
	v_cvt_pk_bf16_f32 v220, v96, v97
	v_cvt_pk_bf16_f32 v221, v98, v99
	v_cvt_pk_bf16_f32 v222, v100, v101
	v_cvt_pk_bf16_f32 v223, v102, v103
	v_cvt_pk_bf16_f32 v224, v104, v105
	v_cvt_pk_bf16_f32 v225, v106, v107
	v_cvt_pk_bf16_f32 v226, v108, v109
	v_cvt_pk_bf16_f32 v227, v110, v111
	global_store_dwordx2 v236, v[220:221], s[34:35] offset:0
	global_store_dwordx2 v236, v[222:223], s[34:35] offset:32
	global_store_dwordx2 v236, v[224:225], s[34:35] offset:64
	global_store_dwordx2 v236, v[226:227], s[34:35] offset:96
	s_add_u32 s34, s34, 0x1000
	s_addc_u32 s35, s35, 0
	v_cvt_pk_bf16_f32 v220, v112, v113
	v_cvt_pk_bf16_f32 v221, v114, v115
	v_cvt_pk_bf16_f32 v222, v116, v117
	v_cvt_pk_bf16_f32 v223, v118, v119
	v_cvt_pk_bf16_f32 v224, v120, v121
	v_cvt_pk_bf16_f32 v225, v122, v123
	v_cvt_pk_bf16_f32 v226, v124, v125
	v_cvt_pk_bf16_f32 v227, v126, v127
	global_store_dwordx2 v236, v[220:221], s[34:35] offset:0
	global_store_dwordx2 v236, v[222:223], s[34:35] offset:32
	global_store_dwordx2 v236, v[224:225], s[34:35] offset:64
	global_store_dwordx2 v236, v[226:227], s[34:35] offset:96
	s_add_u32 s34, s34, 0x1000
	s_addc_u32 s35, s35, 0
	s_sub_u32 s34, s34, 0x8000
	s_subb_u32 s35, s35, 0
	s_and_b32 s28, s29, 63
	s_lshl_b32 s28, s28, 20
	s_add_u32 s40, s94, s28
	s_addc_u32 s41, s95, 0
	s_add_u32 s40, s40, 0x15000000
	s_addc_u32 s41, s41, 0
	s_add_u32 s42, s40, 0x80000
	s_addc_u32 s43, s41, 0
	s_lshr_b32 s28, s29, 6
	s_lshl_b32 s28, s28, 19
	s_add_u32 s44, s94, s28
	s_addc_u32 s45, s95, 0
	s_add_u32 s44, s44, 0x1ca00000
	s_addc_u32 s45, s45, 0
	s_mov_b32 s46, 0xf80
	v_readlane_b32 s39, v242, 45
	s_lshl_b32 s39, s39, 7
	s_and_b32 s39, s39, s46
	s_add_u32 s20, s40, s39
	s_addc_u32 s21, s41, 0
	s_add_u32 s22, s42, s39
	s_addc_u32 s23, s43, 0
	s_add_u32 s24, s44, s39
	s_addc_u32 s25, s45, 0
	s_barrier
	s_add_u32 m0, s26, 0x0
	s_nop 0
	global_load_lds_dwordx4 v244, s[20:21]
	s_add_u32 m0, s26, 0x1000
	s_nop 0
	global_load_lds_dwordx4 v245, s[20:21]
	s_add_u32 m0, s26, 0x2000
	s_nop 0
	global_load_lds_dwordx4 v246, s[20:21]
	s_add_u32 m0, s26, 0x3000
	s_nop 0
	global_load_lds_dwordx4 v247, s[20:21]
	s_add_u32 m0, s26, 0x4000
	s_nop 0
	global_load_lds_dwordx4 v244, s[22:23]
	s_add_u32 m0, s26, 0x5000
	s_nop 0
	global_load_lds_dwordx4 v245, s[22:23]
	s_add_u32 m0, s26, 0x6000
	s_nop 0
	global_load_lds_dwordx4 v246, s[22:23]
	s_add_u32 m0, s26, 0x7000
	s_nop 0
	global_load_lds_dwordx4 v247, s[22:23]
	s_add_u32 m0, s26, 0x8000
	s_nop 0
	global_load_lds_dwordx4 v244, s[24:25]
	s_add_u32 m0, s26, 0x9000
	s_nop 0
	global_load_lds_dwordx4 v245, s[24:25]
	s_add_u32 m0, s26, 0xa000
	s_nop 0
	global_load_lds_dwordx4 v246, s[24:25]
	s_add_u32 m0, s26, 0xb000
	s_nop 0
	global_load_lds_dwordx4 v247, s[24:25]
	s_add_u32 s39, s39, 0x80
	s_and_b32 s39, s39, s46
	s_add_u32 s20, s40, s39
	s_addc_u32 s21, s41, 0
	s_add_u32 s22, s42, s39
	s_addc_u32 s23, s43, 0
	s_add_u32 s24, s44, s39
	s_addc_u32 s25, s45, 0
	v_mov_b32_e32 v0, 0
	v_mov_b32_e32 v1, 0
	v_mov_b32_e32 v2, 0
	v_mov_b32_e32 v3, 0
	v_mov_b32_e32 v4, 0
	v_mov_b32_e32 v5, 0
	v_mov_b32_e32 v6, 0
	v_mov_b32_e32 v7, 0
	v_mov_b32_e32 v8, 0
	v_mov_b32_e32 v9, 0
	v_mov_b32_e32 v10, 0
	v_mov_b32_e32 v11, 0
	v_mov_b32_e32 v12, 0
	v_mov_b32_e32 v13, 0
	v_mov_b32_e32 v14, 0
	v_mov_b32_e32 v15, 0
	v_mov_b32_e32 v16, 0
	v_mov_b32_e32 v17, 0
	v_mov_b32_e32 v18, 0
	v_mov_b32_e32 v19, 0
	v_mov_b32_e32 v20, 0
	v_mov_b32_e32 v21, 0
	v_mov_b32_e32 v22, 0
	v_mov_b32_e32 v23, 0
	v_mov_b32_e32 v24, 0
	v_mov_b32_e32 v25, 0
	v_mov_b32_e32 v26, 0
	v_mov_b32_e32 v27, 0
	v_mov_b32_e32 v28, 0
	v_mov_b32_e32 v29, 0
	v_mov_b32_e32 v30, 0
	v_mov_b32_e32 v31, 0
	v_mov_b32_e32 v32, 0
	v_mov_b32_e32 v33, 0
	v_mov_b32_e32 v34, 0
	v_mov_b32_e32 v35, 0
	v_mov_b32_e32 v36, 0
	v_mov_b32_e32 v37, 0
	v_mov_b32_e32 v38, 0
	v_mov_b32_e32 v39, 0
	v_mov_b32_e32 v40, 0
	v_mov_b32_e32 v41, 0
	v_mov_b32_e32 v42, 0
	v_mov_b32_e32 v43, 0
	v_mov_b32_e32 v44, 0
	v_mov_b32_e32 v45, 0
	v_mov_b32_e32 v46, 0
	v_mov_b32_e32 v47, 0
	v_mov_b32_e32 v48, 0
	v_mov_b32_e32 v49, 0
	v_mov_b32_e32 v50, 0
	v_mov_b32_e32 v51, 0
	v_mov_b32_e32 v52, 0
	v_mov_b32_e32 v53, 0
	v_mov_b32_e32 v54, 0
	v_mov_b32_e32 v55, 0
	v_mov_b32_e32 v56, 0
	v_mov_b32_e32 v57, 0
	v_mov_b32_e32 v58, 0
	v_mov_b32_e32 v59, 0
	v_mov_b32_e32 v60, 0
	v_mov_b32_e32 v61, 0
	v_mov_b32_e32 v62, 0
	v_mov_b32_e32 v63, 0
	v_mov_b32_e32 v64, 0
	v_mov_b32_e32 v65, 0
	v_mov_b32_e32 v66, 0
	v_mov_b32_e32 v67, 0
	v_mov_b32_e32 v68, 0
	v_mov_b32_e32 v69, 0
	v_mov_b32_e32 v70, 0
	v_mov_b32_e32 v71, 0
	v_mov_b32_e32 v72, 0
	v_mov_b32_e32 v73, 0
	v_mov_b32_e32 v74, 0
	v_mov_b32_e32 v75, 0
	v_mov_b32_e32 v76, 0
	v_mov_b32_e32 v77, 0
	v_mov_b32_e32 v78, 0
	v_mov_b32_e32 v79, 0
	v_mov_b32_e32 v80, 0
	v_mov_b32_e32 v81, 0
	v_mov_b32_e32 v82, 0
	v_mov_b32_e32 v83, 0
	v_mov_b32_e32 v84, 0
	v_mov_b32_e32 v85, 0
	v_mov_b32_e32 v86, 0
	v_mov_b32_e32 v87, 0
	v_mov_b32_e32 v88, 0
	v_mov_b32_e32 v89, 0
	v_mov_b32_e32 v90, 0
	v_mov_b32_e32 v91, 0
	v_mov_b32_e32 v92, 0
	v_mov_b32_e32 v93, 0
	v_mov_b32_e32 v94, 0
	v_mov_b32_e32 v95, 0
	v_mov_b32_e32 v96, 0
	v_mov_b32_e32 v97, 0
	v_mov_b32_e32 v98, 0
	v_mov_b32_e32 v99, 0
	v_mov_b32_e32 v100, 0
	v_mov_b32_e32 v101, 0
	v_mov_b32_e32 v102, 0
	v_mov_b32_e32 v103, 0
	v_mov_b32_e32 v104, 0
	v_mov_b32_e32 v105, 0
	v_mov_b32_e32 v106, 0
	v_mov_b32_e32 v107, 0
	v_mov_b32_e32 v108, 0
	v_mov_b32_e32 v109, 0
	v_mov_b32_e32 v110, 0
	v_mov_b32_e32 v111, 0
	v_mov_b32_e32 v112, 0
	v_mov_b32_e32 v113, 0
	v_mov_b32_e32 v114, 0
	v_mov_b32_e32 v115, 0
	v_mov_b32_e32 v116, 0
	v_mov_b32_e32 v117, 0
	v_mov_b32_e32 v118, 0
	v_mov_b32_e32 v119, 0
	v_mov_b32_e32 v120, 0
	v_mov_b32_e32 v121, 0
	v_mov_b32_e32 v122, 0
	v_mov_b32_e32 v123, 0
	v_mov_b32_e32 v124, 0
	v_mov_b32_e32 v125, 0
	v_mov_b32_e32 v126, 0
	v_mov_b32_e32 v127, 0
	s_mov_b32 s27, 0
.Lple_kb:
	s_waitcnt vmcnt(0)
	s_barrier
	ds_read_b128 v[160:163], v198 offset:0
	ds_read_b128 v[164:167], v198 offset:2048
	ds_read_b128 v[168:171], v198 offset:4096
	ds_read_b128 v[172:175], v198 offset:6144
	ds_read_b128 v[128:131], v196 offset:0
	ds_read_b128 v[132:135], v196 offset:2048
	ds_read_b128 v[136:139], v196 offset:4096
	ds_read_b128 v[140:143], v196 offset:6144
	ds_read_b128 v[144:147], v196 offset:8192
	ds_read_b128 v[148:151], v196 offset:10240
	ds_read_b128 v[152:155], v196 offset:12288
	ds_read_b128 v[156:159], v196 offset:14336
	ds_read_b128 v[176:179], v241 offset:0
	ds_read_b128 v[180:183], v241 offset:2048
	ds_read_b128 v[184:187], v241 offset:4096
	ds_read_b128 v[188:191], v241 offset:6144
	ds_read_b128 v[204:207], v197 offset:0
	ds_read_b128 v[208:211], v197 offset:2048
	ds_read_b128 v[212:215], v197 offset:4096
	ds_read_b128 v[216:219], v197 offset:6144
	ds_read_b128 v[220:223], v197 offset:8192
	ds_read_b128 v[224:227], v197 offset:10240
	ds_read_b128 v[228:231], v197 offset:12288
	ds_read_b128 v[232:235], v197 offset:14336
	s_setprio 1
	s_waitcnt lgkmcnt(15)
	v_mfma_f32_16x16x32_bf16 v[0:3], v[160:163], v[128:131], v[0:3]
	v_mfma_f32_16x16x32_bf16 v[4:7], v[164:167], v[128:131], v[4:7]
	v_mfma_f32_16x16x32_bf16 v[8:11], v[168:171], v[128:131], v[8:11]
	v_mfma_f32_16x16x32_bf16 v[12:15], v[172:175], v[128:131], v[12:15]
	s_waitcnt lgkmcnt(15)
	v_mfma_f32_16x16x32_bf16 v[16:19], v[160:163], v[132:135], v[16:19]
	v_mfma_f32_16x16x32_bf16 v[20:23], v[164:167], v[132:135], v[20:23]
	v_mfma_f32_16x16x32_bf16 v[24:27], v[168:171], v[132:135], v[24:27]
	v_mfma_f32_16x16x32_bf16 v[28:31], v[172:175], v[132:135], v[28:31]
	s_waitcnt lgkmcnt(15)
	v_mfma_f32_16x16x32_bf16 v[32:35], v[160:163], v[136:139], v[32:35]
	v_mfma_f32_16x16x32_bf16 v[36:39], v[164:167], v[136:139], v[36:39]
	v_mfma_f32_16x16x32_bf16 v[40:43], v[168:171], v[136:139], v[40:43]
	v_mfma_f32_16x16x32_bf16 v[44:47], v[172:175], v[136:139], v[44:47]
	s_waitcnt lgkmcnt(15)
	v_mfma_f32_16x16x32_bf16 v[48:51], v[160:163], v[140:143], v[48:51]
	v_mfma_f32_16x16x32_bf16 v[52:55], v[164:167], v[140:143], v[52:55]
	v_mfma_f32_16x16x32_bf16 v[56:59], v[168:171], v[140:143], v[56:59]
	v_mfma_f32_16x16x32_bf16 v[60:63], v[172:175], v[140:143], v[60:63]
	s_waitcnt lgkmcnt(15)
	v_mfma_f32_16x16x32_bf16 v[64:67], v[160:163], v[144:147], v[64:67]
	v_mfma_f32_16x16x32_bf16 v[68:71], v[164:167], v[144:147], v[68:71]
	v_mfma_f32_16x16x32_bf16 v[72:75], v[168:171], v[144:147], v[72:75]
	v_mfma_f32_16x16x32_bf16 v[76:79], v[172:175], v[144:147], v[76:79]
	s_waitcnt lgkmcnt(14)
	v_mfma_f32_16x16x32_bf16 v[80:83], v[160:163], v[148:151], v[80:83]
	v_mfma_f32_16x16x32_bf16 v[84:87], v[164:167], v[148:151], v[84:87]
	v_mfma_f32_16x16x32_bf16 v[88:91], v[168:171], v[148:151], v[88:91]
	v_mfma_f32_16x16x32_bf16 v[92:95], v[172:175], v[148:151], v[92:95]
	s_waitcnt lgkmcnt(13)
	v_mfma_f32_16x16x32_bf16 v[96:99], v[160:163], v[152:155], v[96:99]
	v_mfma_f32_16x16x32_bf16 v[100:103], v[164:167], v[152:155], v[100:103]
	v_mfma_f32_16x16x32_bf16 v[104:107], v[168:171], v[152:155], v[104:107]
	v_mfma_f32_16x16x32_bf16 v[108:111], v[172:175], v[152:155], v[108:111]
	s_waitcnt lgkmcnt(12)
	v_mfma_f32_16x16x32_bf16 v[112:115], v[160:163], v[156:159], v[112:115]
	v_mfma_f32_16x16x32_bf16 v[116:119], v[164:167], v[156:159], v[116:119]
	v_mfma_f32_16x16x32_bf16 v[120:123], v[168:171], v[156:159], v[120:123]
	v_mfma_f32_16x16x32_bf16 v[124:127], v[172:175], v[156:159], v[124:127]
	s_setprio 0
	s_waitcnt lgkmcnt(0)
	s_barrier
	s_add_u32 m0, s26, 0x0
	s_nop 0
	global_load_lds_dwordx4 v244, s[20:21]
	s_add_u32 m0, s26, 0x1000
	s_nop 0
	global_load_lds_dwordx4 v245, s[20:21]
	s_add_u32 m0, s26, 0x2000
	s_nop 0
	global_load_lds_dwordx4 v246, s[20:21]
	s_add_u32 m0, s26, 0x3000
	s_nop 0
	global_load_lds_dwordx4 v247, s[20:21]
	s_add_u32 m0, s26, 0x4000
	s_nop 0
	global_load_lds_dwordx4 v244, s[22:23]
	s_add_u32 m0, s26, 0x5000
	s_nop 0
	global_load_lds_dwordx4 v245, s[22:23]
	s_add_u32 m0, s26, 0x6000
	s_nop 0
	global_load_lds_dwordx4 v246, s[22:23]
	s_add_u32 m0, s26, 0x7000
	s_nop 0
	global_load_lds_dwordx4 v247, s[22:23]
	s_add_u32 m0, s26, 0x8000
	s_nop 0
	global_load_lds_dwordx4 v244, s[24:25]
	s_add_u32 m0, s26, 0x9000
	s_nop 0
	global_load_lds_dwordx4 v245, s[24:25]
	s_add_u32 m0, s26, 0xa000
	s_nop 0
	global_load_lds_dwordx4 v246, s[24:25]
	s_add_u32 m0, s26, 0xb000
	s_nop 0
	global_load_lds_dwordx4 v247, s[24:25]
	s_add_u32 s39, s39, 0x80
	s_and_b32 s39, s39, s46
	s_add_u32 s20, s40, s39
	s_addc_u32 s21, s41, 0
	s_add_u32 s22, s42, s39
	s_addc_u32 s23, s43, 0
	s_add_u32 s24, s44, s39
	s_addc_u32 s25, s45, 0
	s_setprio 1
	v_mfma_f32_16x16x32_bf16 v[0:3], v[176:179], v[204:207], v[0:3]
	v_mfma_f32_16x16x32_bf16 v[4:7], v[180:183], v[204:207], v[4:7]
	v_mfma_f32_16x16x32_bf16 v[8:11], v[184:187], v[204:207], v[8:11]
	v_mfma_f32_16x16x32_bf16 v[12:15], v[188:191], v[204:207], v[12:15]
	v_mfma_f32_16x16x32_bf16 v[16:19], v[176:179], v[208:211], v[16:19]
	v_mfma_f32_16x16x32_bf16 v[20:23], v[180:183], v[208:211], v[20:23]
	v_mfma_f32_16x16x32_bf16 v[24:27], v[184:187], v[208:211], v[24:27]
	v_mfma_f32_16x16x32_bf16 v[28:31], v[188:191], v[208:211], v[28:31]
	v_mfma_f32_16x16x32_bf16 v[32:35], v[176:179], v[212:215], v[32:35]
	v_mfma_f32_16x16x32_bf16 v[36:39], v[180:183], v[212:215], v[36:39]
	v_mfma_f32_16x16x32_bf16 v[40:43], v[184:187], v[212:215], v[40:43]
	v_mfma_f32_16x16x32_bf16 v[44:47], v[188:191], v[212:215], v[44:47]
	v_mfma_f32_16x16x32_bf16 v[48:51], v[176:179], v[216:219], v[48:51]
	v_mfma_f32_16x16x32_bf16 v[52:55], v[180:183], v[216:219], v[52:55]
	v_mfma_f32_16x16x32_bf16 v[56:59], v[184:187], v[216:219], v[56:59]
	v_mfma_f32_16x16x32_bf16 v[60:63], v[188:191], v[216:219], v[60:63]
	v_mfma_f32_16x16x32_bf16 v[64:67], v[176:179], v[220:223], v[64:67]
	v_mfma_f32_16x16x32_bf16 v[68:71], v[180:183], v[220:223], v[68:71]
	v_mfma_f32_16x16x32_bf16 v[72:75], v[184:187], v[220:223], v[72:75]
	v_mfma_f32_16x16x32_bf16 v[76:79], v[188:191], v[220:223], v[76:79]
	v_mfma_f32_16x16x32_bf16 v[80:83], v[176:179], v[224:227], v[80:83]
	v_mfma_f32_16x16x32_bf16 v[84:87], v[180:183], v[224:227], v[84:87]
	v_mfma_f32_16x16x32_bf16 v[88:91], v[184:187], v[224:227], v[88:91]
	v_mfma_f32_16x16x32_bf16 v[92:95], v[188:191], v[224:227], v[92:95]
	v_mfma_f32_16x16x32_bf16 v[96:99], v[176:179], v[228:231], v[96:99]
	v_mfma_f32_16x16x32_bf16 v[100:103], v[180:183], v[228:231], v[100:103]
	v_mfma_f32_16x16x32_bf16 v[104:107], v[184:187], v[228:231], v[104:107]
	v_mfma_f32_16x16x32_bf16 v[108:111], v[188:191], v[228:231], v[108:111]
	v_mfma_f32_16x16x32_bf16 v[112:115], v[176:179], v[232:235], v[112:115]
	v_mfma_f32_16x16x32_bf16 v[116:119], v[180:183], v[232:235], v[116:119]
	v_mfma_f32_16x16x32_bf16 v[120:123], v[184:187], v[232:235], v[120:123]
	v_mfma_f32_16x16x32_bf16 v[124:127], v[188:191], v[232:235], v[124:127]
	s_setprio 0
	s_add_i32 s27, s27, 1
	s_cmp_lt_u32 s27, 31
	s_cbranch_scc1 .Lple_kb
	s_waitcnt vmcnt(0)
	s_barrier
	ds_read_b128 v[160:163], v198 offset:0
	ds_read_b128 v[164:167], v198 offset:2048
	ds_read_b128 v[168:171], v198 offset:4096
	ds_read_b128 v[172:175], v198 offset:6144
	ds_read_b128 v[128:131], v196 offset:0
	ds_read_b128 v[132:135], v196 offset:2048
	ds_read_b128 v[136:139], v196 offset:4096
	ds_read_b128 v[140:143], v196 offset:6144
	ds_read_b128 v[144:147], v196 offset:8192
	ds_read_b128 v[148:151], v196 offset:10240
	ds_read_b128 v[152:155], v196 offset:12288
	ds_read_b128 v[156:159], v196 offset:14336
	ds_read_b128 v[176:179], v241 offset:0
	ds_read_b128 v[180:183], v241 offset:2048
	ds_read_b128 v[184:187], v241 offset:4096
	ds_read_b128 v[188:191], v241 offset:6144
	ds_read_b128 v[204:207], v197 offset:0
	ds_read_b128 v[208:211], v197 offset:2048
	ds_read_b128 v[212:215], v197 offset:4096
	ds_read_b128 v[216:219], v197 offset:6144
	ds_read_b128 v[220:223], v197 offset:8192
	ds_read_b128 v[224:227], v197 offset:10240
	ds_read_b128 v[228:231], v197 offset:12288
	ds_read_b128 v[232:235], v197 offset:14336
	s_setprio 1
	s_waitcnt lgkmcnt(15)
	v_mfma_f32_16x16x32_bf16 v[0:3], v[160:163], v[128:131], v[0:3]
	v_mfma_f32_16x16x32_bf16 v[4:7], v[164:167], v[128:131], v[4:7]
	v_mfma_f32_16x16x32_bf16 v[8:11], v[168:171], v[128:131], v[8:11]
	v_mfma_f32_16x16x32_bf16 v[12:15], v[172:175], v[128:131], v[12:15]
	s_waitcnt lgkmcnt(15)
	v_mfma_f32_16x16x32_bf16 v[16:19], v[160:163], v[132:135], v[16:19]
	v_mfma_f32_16x16x32_bf16 v[20:23], v[164:167], v[132:135], v[20:23]
	v_mfma_f32_16x16x32_bf16 v[24:27], v[168:171], v[132:135], v[24:27]
	v_mfma_f32_16x16x32_bf16 v[28:31], v[172:175], v[132:135], v[28:31]
	s_waitcnt lgkmcnt(15)
	v_mfma_f32_16x16x32_bf16 v[32:35], v[160:163], v[136:139], v[32:35]
	v_mfma_f32_16x16x32_bf16 v[36:39], v[164:167], v[136:139], v[36:39]
	v_mfma_f32_16x16x32_bf16 v[40:43], v[168:171], v[136:139], v[40:43]
	v_mfma_f32_16x16x32_bf16 v[44:47], v[172:175], v[136:139], v[44:47]
	s_waitcnt lgkmcnt(15)
	v_mfma_f32_16x16x32_bf16 v[48:51], v[160:163], v[140:143], v[48:51]
	v_mfma_f32_16x16x32_bf16 v[52:55], v[164:167], v[140:143], v[52:55]
	v_mfma_f32_16x16x32_bf16 v[56:59], v[168:171], v[140:143], v[56:59]
	v_mfma_f32_16x16x32_bf16 v[60:63], v[172:175], v[140:143], v[60:63]
	s_waitcnt lgkmcnt(15)
	v_mfma_f32_16x16x32_bf16 v[64:67], v[160:163], v[144:147], v[64:67]
	v_mfma_f32_16x16x32_bf16 v[68:71], v[164:167], v[144:147], v[68:71]
	v_mfma_f32_16x16x32_bf16 v[72:75], v[168:171], v[144:147], v[72:75]
	v_mfma_f32_16x16x32_bf16 v[76:79], v[172:175], v[144:147], v[76:79]
	s_waitcnt lgkmcnt(14)
	v_mfma_f32_16x16x32_bf16 v[80:83], v[160:163], v[148:151], v[80:83]
	v_mfma_f32_16x16x32_bf16 v[84:87], v[164:167], v[148:151], v[84:87]
	v_mfma_f32_16x16x32_bf16 v[88:91], v[168:171], v[148:151], v[88:91]
	v_mfma_f32_16x16x32_bf16 v[92:95], v[172:175], v[148:151], v[92:95]
	s_waitcnt lgkmcnt(13)
	v_mfma_f32_16x16x32_bf16 v[96:99], v[160:163], v[152:155], v[96:99]
	v_mfma_f32_16x16x32_bf16 v[100:103], v[164:167], v[152:155], v[100:103]
	v_mfma_f32_16x16x32_bf16 v[104:107], v[168:171], v[152:155], v[104:107]
	v_mfma_f32_16x16x32_bf16 v[108:111], v[172:175], v[152:155], v[108:111]
	s_waitcnt lgkmcnt(12)
	v_mfma_f32_16x16x32_bf16 v[112:115], v[160:163], v[156:159], v[112:115]
	v_mfma_f32_16x16x32_bf16 v[116:119], v[164:167], v[156:159], v[116:119]
	v_mfma_f32_16x16x32_bf16 v[120:123], v[168:171], v[156:159], v[120:123]
	v_mfma_f32_16x16x32_bf16 v[124:127], v[172:175], v[156:159], v[124:127]
	s_setprio 0
	s_waitcnt lgkmcnt(0)
	s_setprio 1
	v_mfma_f32_16x16x32_bf16 v[0:3], v[176:179], v[204:207], v[0:3]
	v_mfma_f32_16x16x32_bf16 v[4:7], v[180:183], v[204:207], v[4:7]
	v_mfma_f32_16x16x32_bf16 v[8:11], v[184:187], v[204:207], v[8:11]
	v_mfma_f32_16x16x32_bf16 v[12:15], v[188:191], v[204:207], v[12:15]
	v_mfma_f32_16x16x32_bf16 v[16:19], v[176:179], v[208:211], v[16:19]
	v_mfma_f32_16x16x32_bf16 v[20:23], v[180:183], v[208:211], v[20:23]
	v_mfma_f32_16x16x32_bf16 v[24:27], v[184:187], v[208:211], v[24:27]
	v_mfma_f32_16x16x32_bf16 v[28:31], v[188:191], v[208:211], v[28:31]
	v_mfma_f32_16x16x32_bf16 v[32:35], v[176:179], v[212:215], v[32:35]
	v_mfma_f32_16x16x32_bf16 v[36:39], v[180:183], v[212:215], v[36:39]
	v_mfma_f32_16x16x32_bf16 v[40:43], v[184:187], v[212:215], v[40:43]
	v_mfma_f32_16x16x32_bf16 v[44:47], v[188:191], v[212:215], v[44:47]
	v_mfma_f32_16x16x32_bf16 v[48:51], v[176:179], v[216:219], v[48:51]
	v_mfma_f32_16x16x32_bf16 v[52:55], v[180:183], v[216:219], v[52:55]
	v_mfma_f32_16x16x32_bf16 v[56:59], v[184:187], v[216:219], v[56:59]
	v_mfma_f32_16x16x32_bf16 v[60:63], v[188:191], v[216:219], v[60:63]
	v_mfma_f32_16x16x32_bf16 v[64:67], v[176:179], v[220:223], v[64:67]
	v_mfma_f32_16x16x32_bf16 v[68:71], v[180:183], v[220:223], v[68:71]
	v_mfma_f32_16x16x32_bf16 v[72:75], v[184:187], v[220:223], v[72:75]
	v_mfma_f32_16x16x32_bf16 v[76:79], v[188:191], v[220:223], v[76:79]
	v_mfma_f32_16x16x32_bf16 v[80:83], v[176:179], v[224:227], v[80:83]
	v_mfma_f32_16x16x32_bf16 v[84:87], v[180:183], v[224:227], v[84:87]
	v_mfma_f32_16x16x32_bf16 v[88:91], v[184:187], v[224:227], v[88:91]
	v_mfma_f32_16x16x32_bf16 v[92:95], v[188:191], v[224:227], v[92:95]
	v_mfma_f32_16x16x32_bf16 v[96:99], v[176:179], v[228:231], v[96:99]
	v_mfma_f32_16x16x32_bf16 v[100:103], v[180:183], v[228:231], v[100:103]
	v_mfma_f32_16x16x32_bf16 v[104:107], v[184:187], v[228:231], v[104:107]
	v_mfma_f32_16x16x32_bf16 v[108:111], v[188:191], v[228:231], v[108:111]
	v_mfma_f32_16x16x32_bf16 v[112:115], v[176:179], v[232:235], v[112:115]
	v_mfma_f32_16x16x32_bf16 v[116:119], v[180:183], v[232:235], v[116:119]
	v_mfma_f32_16x16x32_bf16 v[120:123], v[184:187], v[232:235], v[120:123]
	v_mfma_f32_16x16x32_bf16 v[124:127], v[188:191], v[232:235], v[124:127]
	s_setprio 0
	s_nop 7
	s_and_b32 s28, s29, 63
	s_lshl_b32 s28, s28, 21
	s_lshr_b32 s2, s29, 6
	s_lshl_b32 s2, s2, 9
	s_add_u32 s28, s28, s2
	s_add_u32 s30, s94, s28
	s_addc_u32 s31, s95, 0
	s_add_u32 s30, s30, 0xd000000
	s_addc_u32 s31, s31, 0
	s_add_u32 s32, s92, s28
	s_addc_u32 s33, s93, 0
	global_load_dwordx4 v[128:131], v203, s[30:31] offset:0
	global_load_dwordx4 v[132:135], v203, s[30:31] offset:64
	global_load_dwordx4 v[136:139], v203, s[30:31] offset:128
	global_load_dwordx4 v[140:143], v203, s[30:31] offset:192
	global_load_dwordx2 v[144:145], v236, s[34:35] offset:0
	global_load_dwordx2 v[146:147], v236, s[34:35] offset:32
	global_load_dwordx2 v[148:149], v236, s[34:35] offset:64
	global_load_dwordx2 v[150:151], v236, s[34:35] offset:96
	s_add_u32 s30, s30, 0x20000
	s_addc_u32 s31, s31, 0
	s_add_u32 s34, s34, 0x1000
	s_addc_u32 s35, s35, 0
	global_load_dwordx4 v[152:155], v203, s[30:31] offset:0
	global_load_dwordx4 v[156:159], v203, s[30:31] offset:64
	global_load_dwordx4 v[160:163], v203, s[30:31] offset:128
	global_load_dwordx4 v[164:167], v203, s[30:31] offset:192
	global_load_dwordx2 v[168:169], v236, s[34:35] offset:0
	global_load_dwordx2 v[170:171], v236, s[34:35] offset:32
	global_load_dwordx2 v[172:173], v236, s[34:35] offset:64
	global_load_dwordx2 v[174:175], v236, s[34:35] offset:96
	s_add_u32 s30, s30, 0x20000
	s_addc_u32 s31, s31, 0
	s_add_u32 s34, s34, 0x1000
	s_addc_u32 s35, s35, 0
	s_waitcnt vmcnt(8)
	v_mul_f32_e32 v176, s36, v0
	v_mul_f32_e32 v177, s36, v1
	v_mul_f32_e32 v178, s36, v2
	v_mul_f32_e32 v179, s36, v3
	v_mul_f32_e32 v180, s36, v4
	v_mul_f32_e32 v181, s36, v5
	v_mul_f32_e32 v182, s36, v6
	v_mul_f32_e32 v183, s36, v7
	v_mul_f32_e32 v184, s36, v8
	v_mul_f32_e32 v185, s36, v9
	v_mul_f32_e32 v186, s36, v10
	v_mul_f32_e32 v187, s36, v11
	v_mul_f32_e32 v188, s36, v12
	v_mul_f32_e32 v189, s36, v13
	v_mul_f32_e32 v190, s36, v14
	v_mul_f32_e32 v191, s36, v15
	v_exp_f32_e32 v176, v176
	v_exp_f32_e32 v177, v177
	v_exp_f32_e32 v178, v178
	v_exp_f32_e32 v179, v179
	v_exp_f32_e32 v180, v180
	v_exp_f32_e32 v181, v181
	v_exp_f32_e32 v182, v182
	v_exp_f32_e32 v183, v183
	v_exp_f32_e32 v184, v184
	v_exp_f32_e32 v185, v185
	v_exp_f32_e32 v186, v186
	v_exp_f32_e32 v187, v187
	v_exp_f32_e32 v188, v188
	v_exp_f32_e32 v189, v189
	v_exp_f32_e32 v190, v190
	v_exp_f32_e32 v191, v191
	v_lshlrev_b32_e32 v0, 16, v144
	v_and_b32_e32 v1, 0xffff0000, v144
	v_lshlrev_b32_e32 v2, 16, v145
	v_and_b32_e32 v3, 0xffff0000, v145
	v_lshlrev_b32_e32 v4, 16, v146
	v_and_b32_e32 v5, 0xffff0000, v146
	v_lshlrev_b32_e32 v6, 16, v147
	v_and_b32_e32 v7, 0xffff0000, v147
	v_lshlrev_b32_e32 v8, 16, v148
	v_and_b32_e32 v9, 0xffff0000, v148
	v_lshlrev_b32_e32 v10, 16, v149
	v_and_b32_e32 v11, 0xffff0000, v149
	v_lshlrev_b32_e32 v12, 16, v150
	v_and_b32_e32 v13, 0xffff0000, v150
	v_lshlrev_b32_e32 v14, 16, v151
	v_and_b32_e32 v15, 0xffff0000, v151
	v_add_f32_e32 v176, 1.0, v176
	v_add_f32_e32 v177, 1.0, v177
	v_add_f32_e32 v178, 1.0, v178
	v_add_f32_e32 v179, 1.0, v179
	v_add_f32_e32 v180, 1.0, v180
	v_add_f32_e32 v181, 1.0, v181
	v_add_f32_e32 v182, 1.0, v182
	v_add_f32_e32 v183, 1.0, v183
	v_add_f32_e32 v184, 1.0, v184
	v_add_f32_e32 v185, 1.0, v185
	v_add_f32_e32 v186, 1.0, v186
	v_add_f32_e32 v187, 1.0, v187
	v_add_f32_e32 v188, 1.0, v188
	v_add_f32_e32 v189, 1.0, v189
	v_add_f32_e32 v190, 1.0, v190
	v_add_f32_e32 v191, 1.0, v191
	v_rcp_f32_e32 v176, v176
	v_rcp_f32_e32 v177, v177
	v_rcp_f32_e32 v178, v178
	v_rcp_f32_e32 v179, v179
	v_rcp_f32_e32 v180, v180
	v_rcp_f32_e32 v181, v181
	v_rcp_f32_e32 v182, v182
	v_rcp_f32_e32 v183, v183
	v_rcp_f32_e32 v184, v184
	v_rcp_f32_e32 v185, v185
	v_rcp_f32_e32 v186, v186
	v_rcp_f32_e32 v187, v187
	v_rcp_f32_e32 v188, v188
	v_rcp_f32_e32 v189, v189
	v_rcp_f32_e32 v190, v190
	v_rcp_f32_e32 v191, v191
	s_nop 0
	v_mul_f32_e32 v176, v176, v0
	v_mul_f32_e32 v177, v177, v1
	v_mul_f32_e32 v178, v178, v2
	v_mul_f32_e32 v179, v179, v3
	v_mul_f32_e32 v180, v180, v4
	v_mul_f32_e32 v181, v181, v5
	v_mul_f32_e32 v182, v182, v6
	v_mul_f32_e32 v183, v183, v7
	v_mul_f32_e32 v184, v184, v8
	v_mul_f32_e32 v185, v185, v9
	v_mul_f32_e32 v186, v186, v10
	v_mul_f32_e32 v187, v187, v11
	v_mul_f32_e32 v188, v188, v12
	v_mul_f32_e32 v189, v189, v13
	v_mul_f32_e32 v190, v190, v14
	v_mul_f32_e32 v191, v191, v15
	v_fma_f32 v128, s37, v128, v176
	v_fma_f32 v129, s37, v129, v177
	v_fma_f32 v130, s37, v130, v178
	v_fma_f32 v131, s37, v131, v179
	v_fma_f32 v132, s37, v132, v180
	v_fma_f32 v133, s37, v133, v181
	v_fma_f32 v134, s37, v134, v182
	v_fma_f32 v135, s37, v135, v183
	v_fma_f32 v136, s37, v136, v184
	v_fma_f32 v137, s37, v137, v185
	v_fma_f32 v138, s37, v138, v186
	v_fma_f32 v139, s37, v139, v187
	v_fma_f32 v140, s37, v140, v188
	v_fma_f32 v141, s37, v141, v189
	v_fma_f32 v142, s37, v142, v190
	v_fma_f32 v143, s37, v143, v191
	global_store_dwordx4 v203, v[128:131], s[32:33] offset:0
	global_store_dwordx4 v203, v[132:135], s[32:33] offset:64
	global_store_dwordx4 v203, v[136:139], s[32:33] offset:128
	global_store_dwordx4 v203, v[140:143], s[32:33] offset:192
	s_add_u32 s32, s32, 0x20000
	s_addc_u32 s33, s33, 0
	global_load_dwordx4 v[128:131], v203, s[30:31] offset:0
	global_load_dwordx4 v[132:135], v203, s[30:31] offset:64
	global_load_dwordx4 v[136:139], v203, s[30:31] offset:128
	global_load_dwordx4 v[140:143], v203, s[30:31] offset:192
	global_load_dwordx2 v[144:145], v236, s[34:35] offset:0
	global_load_dwordx2 v[146:147], v236, s[34:35] offset:32
	global_load_dwordx2 v[148:149], v236, s[34:35] offset:64
	global_load_dwordx2 v[150:151], v236, s[34:35] offset:96
	s_add_u32 s30, s30, 0x20000
	s_addc_u32 s31, s31, 0
	s_add_u32 s34, s34, 0x1000
	s_addc_u32 s35, s35, 0
	s_waitcnt vmcnt(12)
	v_mul_f32_e32 v176, s36, v16
	v_mul_f32_e32 v177, s36, v17
	v_mul_f32_e32 v178, s36, v18
	v_mul_f32_e32 v179, s36, v19
	v_mul_f32_e32 v180, s36, v20
	v_mul_f32_e32 v181, s36, v21
	v_mul_f32_e32 v182, s36, v22
	v_mul_f32_e32 v183, s36, v23
	v_mul_f32_e32 v184, s36, v24
	v_mul_f32_e32 v185, s36, v25
	v_mul_f32_e32 v186, s36, v26
	v_mul_f32_e32 v187, s36, v27
	v_mul_f32_e32 v188, s36, v28
	v_mul_f32_e32 v189, s36, v29
	v_mul_f32_e32 v190, s36, v30
	v_mul_f32_e32 v191, s36, v31
	v_exp_f32_e32 v176, v176
	v_exp_f32_e32 v177, v177
	v_exp_f32_e32 v178, v178
	v_exp_f32_e32 v179, v179
	v_exp_f32_e32 v180, v180
	v_exp_f32_e32 v181, v181
	v_exp_f32_e32 v182, v182
	v_exp_f32_e32 v183, v183
	v_exp_f32_e32 v184, v184
	v_exp_f32_e32 v185, v185
	v_exp_f32_e32 v186, v186
	v_exp_f32_e32 v187, v187
	v_exp_f32_e32 v188, v188
	v_exp_f32_e32 v189, v189
	v_exp_f32_e32 v190, v190
	v_exp_f32_e32 v191, v191
	v_lshlrev_b32_e32 v16, 16, v168
	v_and_b32_e32 v17, 0xffff0000, v168
	v_lshlrev_b32_e32 v18, 16, v169
	v_and_b32_e32 v19, 0xffff0000, v169
	v_lshlrev_b32_e32 v20, 16, v170
	v_and_b32_e32 v21, 0xffff0000, v170
	v_lshlrev_b32_e32 v22, 16, v171
	v_and_b32_e32 v23, 0xffff0000, v171
	v_lshlrev_b32_e32 v24, 16, v172
	v_and_b32_e32 v25, 0xffff0000, v172
	v_lshlrev_b32_e32 v26, 16, v173
	v_and_b32_e32 v27, 0xffff0000, v173
	v_lshlrev_b32_e32 v28, 16, v174
	v_and_b32_e32 v29, 0xffff0000, v174
	v_lshlrev_b32_e32 v30, 16, v175
	v_and_b32_e32 v31, 0xffff0000, v175
	v_add_f32_e32 v176, 1.0, v176
	v_add_f32_e32 v177, 1.0, v177
	v_add_f32_e32 v178, 1.0, v178
	v_add_f32_e32 v179, 1.0, v179
	v_add_f32_e32 v180, 1.0, v180
	v_add_f32_e32 v181, 1.0, v181
	v_add_f32_e32 v182, 1.0, v182
	v_add_f32_e32 v183, 1.0, v183
	v_add_f32_e32 v184, 1.0, v184
	v_add_f32_e32 v185, 1.0, v185
	v_add_f32_e32 v186, 1.0, v186
	v_add_f32_e32 v187, 1.0, v187
	v_add_f32_e32 v188, 1.0, v188
	v_add_f32_e32 v189, 1.0, v189
	v_add_f32_e32 v190, 1.0, v190
	v_add_f32_e32 v191, 1.0, v191
	v_rcp_f32_e32 v176, v176
	v_rcp_f32_e32 v177, v177
	v_rcp_f32_e32 v178, v178
	v_rcp_f32_e32 v179, v179
	v_rcp_f32_e32 v180, v180
	v_rcp_f32_e32 v181, v181
	v_rcp_f32_e32 v182, v182
	v_rcp_f32_e32 v183, v183
	v_rcp_f32_e32 v184, v184
	v_rcp_f32_e32 v185, v185
	v_rcp_f32_e32 v186, v186
	v_rcp_f32_e32 v187, v187
	v_rcp_f32_e32 v188, v188
	v_rcp_f32_e32 v189, v189
	v_rcp_f32_e32 v190, v190
	v_rcp_f32_e32 v191, v191
	s_nop 0
	v_mul_f32_e32 v176, v176, v16
	v_mul_f32_e32 v177, v177, v17
	v_mul_f32_e32 v178, v178, v18
	v_mul_f32_e32 v179, v179, v19
	v_mul_f32_e32 v180, v180, v20
	v_mul_f32_e32 v181, v181, v21
	v_mul_f32_e32 v182, v182, v22
	v_mul_f32_e32 v183, v183, v23
	v_mul_f32_e32 v184, v184, v24
	v_mul_f32_e32 v185, v185, v25
	v_mul_f32_e32 v186, v186, v26
	v_mul_f32_e32 v187, v187, v27
	v_mul_f32_e32 v188, v188, v28
	v_mul_f32_e32 v189, v189, v29
	v_mul_f32_e32 v190, v190, v30
	v_mul_f32_e32 v191, v191, v31
	v_fma_f32 v152, s37, v152, v176
	v_fma_f32 v153, s37, v153, v177
	v_fma_f32 v154, s37, v154, v178
	v_fma_f32 v155, s37, v155, v179
	v_fma_f32 v156, s37, v156, v180
	v_fma_f32 v157, s37, v157, v181
	v_fma_f32 v158, s37, v158, v182
	v_fma_f32 v159, s37, v159, v183
	v_fma_f32 v160, s37, v160, v184
	v_fma_f32 v161, s37, v161, v185
	v_fma_f32 v162, s37, v162, v186
	v_fma_f32 v163, s37, v163, v187
	v_fma_f32 v164, s37, v164, v188
	v_fma_f32 v165, s37, v165, v189
	v_fma_f32 v166, s37, v166, v190
	v_fma_f32 v167, s37, v167, v191
	global_store_dwordx4 v203, v[152:155], s[32:33] offset:0
	global_store_dwordx4 v203, v[156:159], s[32:33] offset:64
	global_store_dwordx4 v203, v[160:163], s[32:33] offset:128
	global_store_dwordx4 v203, v[164:167], s[32:33] offset:192
	s_add_u32 s32, s32, 0x20000
	s_addc_u32 s33, s33, 0
	global_load_dwordx4 v[152:155], v203, s[30:31] offset:0
	global_load_dwordx4 v[156:159], v203, s[30:31] offset:64
	global_load_dwordx4 v[160:163], v203, s[30:31] offset:128
	global_load_dwordx4 v[164:167], v203, s[30:31] offset:192
	global_load_dwordx2 v[168:169], v236, s[34:35] offset:0
	global_load_dwordx2 v[170:171], v236, s[34:35] offset:32
	global_load_dwordx2 v[172:173], v236, s[34:35] offset:64
	global_load_dwordx2 v[174:175], v236, s[34:35] offset:96
	s_add_u32 s30, s30, 0x20000
	s_addc_u32 s31, s31, 0
	s_add_u32 s34, s34, 0x1000
	s_addc_u32 s35, s35, 0
	s_waitcnt vmcnt(12)
	v_mul_f32_e32 v176, s36, v32
	v_mul_f32_e32 v177, s36, v33
	v_mul_f32_e32 v178, s36, v34
	v_mul_f32_e32 v179, s36, v35
	v_mul_f32_e32 v180, s36, v36
	v_mul_f32_e32 v181, s36, v37
	v_mul_f32_e32 v182, s36, v38
	v_mul_f32_e32 v183, s36, v39
	v_mul_f32_e32 v184, s36, v40
	v_mul_f32_e32 v185, s36, v41
	v_mul_f32_e32 v186, s36, v42
	v_mul_f32_e32 v187, s36, v43
	v_mul_f32_e32 v188, s36, v44
	v_mul_f32_e32 v189, s36, v45
	v_mul_f32_e32 v190, s36, v46
	v_mul_f32_e32 v191, s36, v47
	v_exp_f32_e32 v176, v176
	v_exp_f32_e32 v177, v177
	v_exp_f32_e32 v178, v178
	v_exp_f32_e32 v179, v179
	v_exp_f32_e32 v180, v180
	v_exp_f32_e32 v181, v181
	v_exp_f32_e32 v182, v182
	v_exp_f32_e32 v183, v183
	v_exp_f32_e32 v184, v184
	v_exp_f32_e32 v185, v185
	v_exp_f32_e32 v186, v186
	v_exp_f32_e32 v187, v187
	v_exp_f32_e32 v188, v188
	v_exp_f32_e32 v189, v189
	v_exp_f32_e32 v190, v190
	v_exp_f32_e32 v191, v191
	v_lshlrev_b32_e32 v32, 16, v144
	v_and_b32_e32 v33, 0xffff0000, v144
	v_lshlrev_b32_e32 v34, 16, v145
	v_and_b32_e32 v35, 0xffff0000, v145
	v_lshlrev_b32_e32 v36, 16, v146
	v_and_b32_e32 v37, 0xffff0000, v146
	v_lshlrev_b32_e32 v38, 16, v147
	v_and_b32_e32 v39, 0xffff0000, v147
	v_lshlrev_b32_e32 v40, 16, v148
	v_and_b32_e32 v41, 0xffff0000, v148
	v_lshlrev_b32_e32 v42, 16, v149
	v_and_b32_e32 v43, 0xffff0000, v149
	v_lshlrev_b32_e32 v44, 16, v150
	v_and_b32_e32 v45, 0xffff0000, v150
	v_lshlrev_b32_e32 v46, 16, v151
	v_and_b32_e32 v47, 0xffff0000, v151
	v_add_f32_e32 v176, 1.0, v176
	v_add_f32_e32 v177, 1.0, v177
	v_add_f32_e32 v178, 1.0, v178
	v_add_f32_e32 v179, 1.0, v179
	v_add_f32_e32 v180, 1.0, v180
	v_add_f32_e32 v181, 1.0, v181
	v_add_f32_e32 v182, 1.0, v182
	v_add_f32_e32 v183, 1.0, v183
	v_add_f32_e32 v184, 1.0, v184
	v_add_f32_e32 v185, 1.0, v185
	v_add_f32_e32 v186, 1.0, v186
	v_add_f32_e32 v187, 1.0, v187
	v_add_f32_e32 v188, 1.0, v188
	v_add_f32_e32 v189, 1.0, v189
	v_add_f32_e32 v190, 1.0, v190
	v_add_f32_e32 v191, 1.0, v191
	v_rcp_f32_e32 v176, v176
	v_rcp_f32_e32 v177, v177
	v_rcp_f32_e32 v178, v178
	v_rcp_f32_e32 v179, v179
	v_rcp_f32_e32 v180, v180
	v_rcp_f32_e32 v181, v181
	v_rcp_f32_e32 v182, v182
	v_rcp_f32_e32 v183, v183
	v_rcp_f32_e32 v184, v184
	v_rcp_f32_e32 v185, v185
	v_rcp_f32_e32 v186, v186
	v_rcp_f32_e32 v187, v187
	v_rcp_f32_e32 v188, v188
	v_rcp_f32_e32 v189, v189
	v_rcp_f32_e32 v190, v190
	v_rcp_f32_e32 v191, v191
	s_nop 0
	v_mul_f32_e32 v176, v176, v32
	v_mul_f32_e32 v177, v177, v33
	v_mul_f32_e32 v178, v178, v34
	v_mul_f32_e32 v179, v179, v35
	v_mul_f32_e32 v180, v180, v36
	v_mul_f32_e32 v181, v181, v37
	v_mul_f32_e32 v182, v182, v38
	v_mul_f32_e32 v183, v183, v39
	v_mul_f32_e32 v184, v184, v40
	v_mul_f32_e32 v185, v185, v41
	v_mul_f32_e32 v186, v186, v42
	v_mul_f32_e32 v187, v187, v43
	v_mul_f32_e32 v188, v188, v44
	v_mul_f32_e32 v189, v189, v45
	v_mul_f32_e32 v190, v190, v46
	v_mul_f32_e32 v191, v191, v47
	v_fma_f32 v128, s37, v128, v176
	v_fma_f32 v129, s37, v129, v177
	v_fma_f32 v130, s37, v130, v178
	v_fma_f32 v131, s37, v131, v179
	v_fma_f32 v132, s37, v132, v180
	v_fma_f32 v133, s37, v133, v181
	v_fma_f32 v134, s37, v134, v182
	v_fma_f32 v135, s37, v135, v183
	v_fma_f32 v136, s37, v136, v184
	v_fma_f32 v137, s37, v137, v185
	v_fma_f32 v138, s37, v138, v186
	v_fma_f32 v139, s37, v139, v187
	v_fma_f32 v140, s37, v140, v188
	v_fma_f32 v141, s37, v141, v189
	v_fma_f32 v142, s37, v142, v190
	v_fma_f32 v143, s37, v143, v191
	global_store_dwordx4 v203, v[128:131], s[32:33] offset:0
	global_store_dwordx4 v203, v[132:135], s[32:33] offset:64
	global_store_dwordx4 v203, v[136:139], s[32:33] offset:128
	global_store_dwordx4 v203, v[140:143], s[32:33] offset:192
	s_add_u32 s32, s32, 0x20000
	s_addc_u32 s33, s33, 0
	global_load_dwordx4 v[128:131], v203, s[30:31] offset:0
	global_load_dwordx4 v[132:135], v203, s[30:31] offset:64
	global_load_dwordx4 v[136:139], v203, s[30:31] offset:128
	global_load_dwordx4 v[140:143], v203, s[30:31] offset:192
	global_load_dwordx2 v[144:145], v236, s[34:35] offset:0
	global_load_dwordx2 v[146:147], v236, s[34:35] offset:32
	global_load_dwordx2 v[148:149], v236, s[34:35] offset:64
	global_load_dwordx2 v[150:151], v236, s[34:35] offset:96
	s_add_u32 s30, s30, 0x20000
	s_addc_u32 s31, s31, 0
	s_add_u32 s34, s34, 0x1000
	s_addc_u32 s35, s35, 0
	s_waitcnt vmcnt(12)
	v_mul_f32_e32 v176, s36, v48
	v_mul_f32_e32 v177, s36, v49
	v_mul_f32_e32 v178, s36, v50
	v_mul_f32_e32 v179, s36, v51
	v_mul_f32_e32 v180, s36, v52
	v_mul_f32_e32 v181, s36, v53
	v_mul_f32_e32 v182, s36, v54
	v_mul_f32_e32 v183, s36, v55
	v_mul_f32_e32 v184, s36, v56
	v_mul_f32_e32 v185, s36, v57
	v_mul_f32_e32 v186, s36, v58
	v_mul_f32_e32 v187, s36, v59
	v_mul_f32_e32 v188, s36, v60
	v_mul_f32_e32 v189, s36, v61
	v_mul_f32_e32 v190, s36, v62
	v_mul_f32_e32 v191, s36, v63
	v_exp_f32_e32 v176, v176
	v_exp_f32_e32 v177, v177
	v_exp_f32_e32 v178, v178
	v_exp_f32_e32 v179, v179
	v_exp_f32_e32 v180, v180
	v_exp_f32_e32 v181, v181
	v_exp_f32_e32 v182, v182
	v_exp_f32_e32 v183, v183
	v_exp_f32_e32 v184, v184
	v_exp_f32_e32 v185, v185
	v_exp_f32_e32 v186, v186
	v_exp_f32_e32 v187, v187
	v_exp_f32_e32 v188, v188
	v_exp_f32_e32 v189, v189
	v_exp_f32_e32 v190, v190
	v_exp_f32_e32 v191, v191
	v_lshlrev_b32_e32 v48, 16, v168
	v_and_b32_e32 v49, 0xffff0000, v168
	v_lshlrev_b32_e32 v50, 16, v169
	v_and_b32_e32 v51, 0xffff0000, v169
	v_lshlrev_b32_e32 v52, 16, v170
	v_and_b32_e32 v53, 0xffff0000, v170
	v_lshlrev_b32_e32 v54, 16, v171
	v_and_b32_e32 v55, 0xffff0000, v171
	v_lshlrev_b32_e32 v56, 16, v172
	v_and_b32_e32 v57, 0xffff0000, v172
	v_lshlrev_b32_e32 v58, 16, v173
	v_and_b32_e32 v59, 0xffff0000, v173
	v_lshlrev_b32_e32 v60, 16, v174
	v_and_b32_e32 v61, 0xffff0000, v174
	v_lshlrev_b32_e32 v62, 16, v175
	v_and_b32_e32 v63, 0xffff0000, v175
	v_add_f32_e32 v176, 1.0, v176
	v_add_f32_e32 v177, 1.0, v177
	v_add_f32_e32 v178, 1.0, v178
	v_add_f32_e32 v179, 1.0, v179
	v_add_f32_e32 v180, 1.0, v180
	v_add_f32_e32 v181, 1.0, v181
	v_add_f32_e32 v182, 1.0, v182
	v_add_f32_e32 v183, 1.0, v183
	v_add_f32_e32 v184, 1.0, v184
	v_add_f32_e32 v185, 1.0, v185
	v_add_f32_e32 v186, 1.0, v186
	v_add_f32_e32 v187, 1.0, v187
	v_add_f32_e32 v188, 1.0, v188
	v_add_f32_e32 v189, 1.0, v189
	v_add_f32_e32 v190, 1.0, v190
	v_add_f32_e32 v191, 1.0, v191
	v_rcp_f32_e32 v176, v176
	v_rcp_f32_e32 v177, v177
	v_rcp_f32_e32 v178, v178
	v_rcp_f32_e32 v179, v179
	v_rcp_f32_e32 v180, v180
	v_rcp_f32_e32 v181, v181
	v_rcp_f32_e32 v182, v182
	v_rcp_f32_e32 v183, v183
	v_rcp_f32_e32 v184, v184
	v_rcp_f32_e32 v185, v185
	v_rcp_f32_e32 v186, v186
	v_rcp_f32_e32 v187, v187
	v_rcp_f32_e32 v188, v188
	v_rcp_f32_e32 v189, v189
	v_rcp_f32_e32 v190, v190
	v_rcp_f32_e32 v191, v191
	s_nop 0
	v_mul_f32_e32 v176, v176, v48
	v_mul_f32_e32 v177, v177, v49
	v_mul_f32_e32 v178, v178, v50
	v_mul_f32_e32 v179, v179, v51
	v_mul_f32_e32 v180, v180, v52
	v_mul_f32_e32 v181, v181, v53
	v_mul_f32_e32 v182, v182, v54
	v_mul_f32_e32 v183, v183, v55
	v_mul_f32_e32 v184, v184, v56
	v_mul_f32_e32 v185, v185, v57
	v_mul_f32_e32 v186, v186, v58
	v_mul_f32_e32 v187, v187, v59
	v_mul_f32_e32 v188, v188, v60
	v_mul_f32_e32 v189, v189, v61
	v_mul_f32_e32 v190, v190, v62
	v_mul_f32_e32 v191, v191, v63
	v_fma_f32 v152, s37, v152, v176
	v_fma_f32 v153, s37, v153, v177
	v_fma_f32 v154, s37, v154, v178
	v_fma_f32 v155, s37, v155, v179
	v_fma_f32 v156, s37, v156, v180
	v_fma_f32 v157, s37, v157, v181
	v_fma_f32 v158, s37, v158, v182
	v_fma_f32 v159, s37, v159, v183
	v_fma_f32 v160, s37, v160, v184
	v_fma_f32 v161, s37, v161, v185
	v_fma_f32 v162, s37, v162, v186
	v_fma_f32 v163, s37, v163, v187
	v_fma_f32 v164, s37, v164, v188
	v_fma_f32 v165, s37, v165, v189
	v_fma_f32 v166, s37, v166, v190
	v_fma_f32 v167, s37, v167, v191
	global_store_dwordx4 v203, v[152:155], s[32:33] offset:0
	global_store_dwordx4 v203, v[156:159], s[32:33] offset:64
	global_store_dwordx4 v203, v[160:163], s[32:33] offset:128
	global_store_dwordx4 v203, v[164:167], s[32:33] offset:192
	s_add_u32 s32, s32, 0x20000
	s_addc_u32 s33, s33, 0
	global_load_dwordx4 v[152:155], v203, s[30:31] offset:0
	global_load_dwordx4 v[156:159], v203, s[30:31] offset:64
	global_load_dwordx4 v[160:163], v203, s[30:31] offset:128
	global_load_dwordx4 v[164:167], v203, s[30:31] offset:192
	global_load_dwordx2 v[168:169], v236, s[34:35] offset:0
	global_load_dwordx2 v[170:171], v236, s[34:35] offset:32
	global_load_dwordx2 v[172:173], v236, s[34:35] offset:64
	global_load_dwordx2 v[174:175], v236, s[34:35] offset:96
	s_add_u32 s30, s30, 0x20000
	s_addc_u32 s31, s31, 0
	s_add_u32 s34, s34, 0x1000
	s_addc_u32 s35, s35, 0
	s_waitcnt vmcnt(12)
	v_mul_f32_e32 v176, s36, v64
	v_mul_f32_e32 v177, s36, v65
	v_mul_f32_e32 v178, s36, v66
	v_mul_f32_e32 v179, s36, v67
	v_mul_f32_e32 v180, s36, v68
	v_mul_f32_e32 v181, s36, v69
	v_mul_f32_e32 v182, s36, v70
	v_mul_f32_e32 v183, s36, v71
	v_mul_f32_e32 v184, s36, v72
	v_mul_f32_e32 v185, s36, v73
	v_mul_f32_e32 v186, s36, v74
	v_mul_f32_e32 v187, s36, v75
	v_mul_f32_e32 v188, s36, v76
	v_mul_f32_e32 v189, s36, v77
	v_mul_f32_e32 v190, s36, v78
	v_mul_f32_e32 v191, s36, v79
	v_exp_f32_e32 v176, v176
	v_exp_f32_e32 v177, v177
	v_exp_f32_e32 v178, v178
	v_exp_f32_e32 v179, v179
	v_exp_f32_e32 v180, v180
	v_exp_f32_e32 v181, v181
	v_exp_f32_e32 v182, v182
	v_exp_f32_e32 v183, v183
	v_exp_f32_e32 v184, v184
	v_exp_f32_e32 v185, v185
	v_exp_f32_e32 v186, v186
	v_exp_f32_e32 v187, v187
	v_exp_f32_e32 v188, v188
	v_exp_f32_e32 v189, v189
	v_exp_f32_e32 v190, v190
	v_exp_f32_e32 v191, v191
	v_lshlrev_b32_e32 v64, 16, v144
	v_and_b32_e32 v65, 0xffff0000, v144
	v_lshlrev_b32_e32 v66, 16, v145
	v_and_b32_e32 v67, 0xffff0000, v145
	v_lshlrev_b32_e32 v68, 16, v146
	v_and_b32_e32 v69, 0xffff0000, v146
	v_lshlrev_b32_e32 v70, 16, v147
	v_and_b32_e32 v71, 0xffff0000, v147
	v_lshlrev_b32_e32 v72, 16, v148
	v_and_b32_e32 v73, 0xffff0000, v148
	v_lshlrev_b32_e32 v74, 16, v149
	v_and_b32_e32 v75, 0xffff0000, v149
	v_lshlrev_b32_e32 v76, 16, v150
	v_and_b32_e32 v77, 0xffff0000, v150
	v_lshlrev_b32_e32 v78, 16, v151
	v_and_b32_e32 v79, 0xffff0000, v151
	v_add_f32_e32 v176, 1.0, v176
	v_add_f32_e32 v177, 1.0, v177
	v_add_f32_e32 v178, 1.0, v178
	v_add_f32_e32 v179, 1.0, v179
	v_add_f32_e32 v180, 1.0, v180
	v_add_f32_e32 v181, 1.0, v181
	v_add_f32_e32 v182, 1.0, v182
	v_add_f32_e32 v183, 1.0, v183
	v_add_f32_e32 v184, 1.0, v184
	v_add_f32_e32 v185, 1.0, v185
	v_add_f32_e32 v186, 1.0, v186
	v_add_f32_e32 v187, 1.0, v187
	v_add_f32_e32 v188, 1.0, v188
	v_add_f32_e32 v189, 1.0, v189
	v_add_f32_e32 v190, 1.0, v190
	v_add_f32_e32 v191, 1.0, v191
	v_rcp_f32_e32 v176, v176
	v_rcp_f32_e32 v177, v177
	v_rcp_f32_e32 v178, v178
	v_rcp_f32_e32 v179, v179
	v_rcp_f32_e32 v180, v180
	v_rcp_f32_e32 v181, v181
	v_rcp_f32_e32 v182, v182
	v_rcp_f32_e32 v183, v183
	v_rcp_f32_e32 v184, v184
	v_rcp_f32_e32 v185, v185
	v_rcp_f32_e32 v186, v186
	v_rcp_f32_e32 v187, v187
	v_rcp_f32_e32 v188, v188
	v_rcp_f32_e32 v189, v189
	v_rcp_f32_e32 v190, v190
	v_rcp_f32_e32 v191, v191
	s_nop 0
	v_mul_f32_e32 v176, v176, v64
	v_mul_f32_e32 v177, v177, v65
	v_mul_f32_e32 v178, v178, v66
	v_mul_f32_e32 v179, v179, v67
	v_mul_f32_e32 v180, v180, v68
	v_mul_f32_e32 v181, v181, v69
	v_mul_f32_e32 v182, v182, v70
	v_mul_f32_e32 v183, v183, v71
	v_mul_f32_e32 v184, v184, v72
	v_mul_f32_e32 v185, v185, v73
	v_mul_f32_e32 v186, v186, v74
	v_mul_f32_e32 v187, v187, v75
	v_mul_f32_e32 v188, v188, v76
	v_mul_f32_e32 v189, v189, v77
	v_mul_f32_e32 v190, v190, v78
	v_mul_f32_e32 v191, v191, v79
	v_fma_f32 v128, s37, v128, v176
	v_fma_f32 v129, s37, v129, v177
	v_fma_f32 v130, s37, v130, v178
	v_fma_f32 v131, s37, v131, v179
	v_fma_f32 v132, s37, v132, v180
	v_fma_f32 v133, s37, v133, v181
	v_fma_f32 v134, s37, v134, v182
	v_fma_f32 v135, s37, v135, v183
	v_fma_f32 v136, s37, v136, v184
	v_fma_f32 v137, s37, v137, v185
	v_fma_f32 v138, s37, v138, v186
	v_fma_f32 v139, s37, v139, v187
	v_fma_f32 v140, s37, v140, v188
	v_fma_f32 v141, s37, v141, v189
	v_fma_f32 v142, s37, v142, v190
	v_fma_f32 v143, s37, v143, v191
	global_store_dwordx4 v203, v[128:131], s[32:33] offset:0
	global_store_dwordx4 v203, v[132:135], s[32:33] offset:64
	global_store_dwordx4 v203, v[136:139], s[32:33] offset:128
	global_store_dwordx4 v203, v[140:143], s[32:33] offset:192
	s_add_u32 s32, s32, 0x20000
	s_addc_u32 s33, s33, 0
	global_load_dwordx4 v[128:131], v203, s[30:31] offset:0
	global_load_dwordx4 v[132:135], v203, s[30:31] offset:64
	global_load_dwordx4 v[136:139], v203, s[30:31] offset:128
	global_load_dwordx4 v[140:143], v203, s[30:31] offset:192
	global_load_dwordx2 v[144:145], v236, s[34:35] offset:0
	global_load_dwordx2 v[146:147], v236, s[34:35] offset:32
	global_load_dwordx2 v[148:149], v236, s[34:35] offset:64
	global_load_dwordx2 v[150:151], v236, s[34:35] offset:96
	s_add_u32 s30, s30, 0x20000
	s_addc_u32 s31, s31, 0
	s_add_u32 s34, s34, 0x1000
	s_addc_u32 s35, s35, 0
	s_waitcnt vmcnt(12)
	v_mul_f32_e32 v176, s36, v80
	v_mul_f32_e32 v177, s36, v81
	v_mul_f32_e32 v178, s36, v82
	v_mul_f32_e32 v179, s36, v83
	v_mul_f32_e32 v180, s36, v84
	v_mul_f32_e32 v181, s36, v85
	v_mul_f32_e32 v182, s36, v86
	v_mul_f32_e32 v183, s36, v87
	v_mul_f32_e32 v184, s36, v88
	v_mul_f32_e32 v185, s36, v89
	v_mul_f32_e32 v186, s36, v90
	v_mul_f32_e32 v187, s36, v91
	v_mul_f32_e32 v188, s36, v92
	v_mul_f32_e32 v189, s36, v93
	v_mul_f32_e32 v190, s36, v94
	v_mul_f32_e32 v191, s36, v95
	v_exp_f32_e32 v176, v176
	v_exp_f32_e32 v177, v177
	v_exp_f32_e32 v178, v178
	v_exp_f32_e32 v179, v179
	v_exp_f32_e32 v180, v180
	v_exp_f32_e32 v181, v181
	v_exp_f32_e32 v182, v182
	v_exp_f32_e32 v183, v183
	v_exp_f32_e32 v184, v184
	v_exp_f32_e32 v185, v185
	v_exp_f32_e32 v186, v186
	v_exp_f32_e32 v187, v187
	v_exp_f32_e32 v188, v188
	v_exp_f32_e32 v189, v189
	v_exp_f32_e32 v190, v190
	v_exp_f32_e32 v191, v191
	v_lshlrev_b32_e32 v80, 16, v168
	v_and_b32_e32 v81, 0xffff0000, v168
	v_lshlrev_b32_e32 v82, 16, v169
	v_and_b32_e32 v83, 0xffff0000, v169
	v_lshlrev_b32_e32 v84, 16, v170
	v_and_b32_e32 v85, 0xffff0000, v170
	v_lshlrev_b32_e32 v86, 16, v171
	v_and_b32_e32 v87, 0xffff0000, v171
	v_lshlrev_b32_e32 v88, 16, v172
	v_and_b32_e32 v89, 0xffff0000, v172
	v_lshlrev_b32_e32 v90, 16, v173
	v_and_b32_e32 v91, 0xffff0000, v173
	v_lshlrev_b32_e32 v92, 16, v174
	v_and_b32_e32 v93, 0xffff0000, v174
	v_lshlrev_b32_e32 v94, 16, v175
	v_and_b32_e32 v95, 0xffff0000, v175
	v_add_f32_e32 v176, 1.0, v176
	v_add_f32_e32 v177, 1.0, v177
	v_add_f32_e32 v178, 1.0, v178
	v_add_f32_e32 v179, 1.0, v179
	v_add_f32_e32 v180, 1.0, v180
	v_add_f32_e32 v181, 1.0, v181
	v_add_f32_e32 v182, 1.0, v182
	v_add_f32_e32 v183, 1.0, v183
	v_add_f32_e32 v184, 1.0, v184
	v_add_f32_e32 v185, 1.0, v185
	v_add_f32_e32 v186, 1.0, v186
	v_add_f32_e32 v187, 1.0, v187
	v_add_f32_e32 v188, 1.0, v188
	v_add_f32_e32 v189, 1.0, v189
	v_add_f32_e32 v190, 1.0, v190
	v_add_f32_e32 v191, 1.0, v191
	v_rcp_f32_e32 v176, v176
	v_rcp_f32_e32 v177, v177
	v_rcp_f32_e32 v178, v178
	v_rcp_f32_e32 v179, v179
	v_rcp_f32_e32 v180, v180
	v_rcp_f32_e32 v181, v181
	v_rcp_f32_e32 v182, v182
	v_rcp_f32_e32 v183, v183
	v_rcp_f32_e32 v184, v184
	v_rcp_f32_e32 v185, v185
	v_rcp_f32_e32 v186, v186
	v_rcp_f32_e32 v187, v187
	v_rcp_f32_e32 v188, v188
	v_rcp_f32_e32 v189, v189
	v_rcp_f32_e32 v190, v190
	v_rcp_f32_e32 v191, v191
	s_nop 0
	v_mul_f32_e32 v176, v176, v80
	v_mul_f32_e32 v177, v177, v81
	v_mul_f32_e32 v178, v178, v82
	v_mul_f32_e32 v179, v179, v83
	v_mul_f32_e32 v180, v180, v84
	v_mul_f32_e32 v181, v181, v85
	v_mul_f32_e32 v182, v182, v86
	v_mul_f32_e32 v183, v183, v87
	v_mul_f32_e32 v184, v184, v88
	v_mul_f32_e32 v185, v185, v89
	v_mul_f32_e32 v186, v186, v90
	v_mul_f32_e32 v187, v187, v91
	v_mul_f32_e32 v188, v188, v92
	v_mul_f32_e32 v189, v189, v93
	v_mul_f32_e32 v190, v190, v94
	v_mul_f32_e32 v191, v191, v95
	v_fma_f32 v152, s37, v152, v176
	v_fma_f32 v153, s37, v153, v177
	v_fma_f32 v154, s37, v154, v178
	v_fma_f32 v155, s37, v155, v179
	v_fma_f32 v156, s37, v156, v180
	v_fma_f32 v157, s37, v157, v181
	v_fma_f32 v158, s37, v158, v182
	v_fma_f32 v159, s37, v159, v183
	v_fma_f32 v160, s37, v160, v184
	v_fma_f32 v161, s37, v161, v185
	v_fma_f32 v162, s37, v162, v186
	v_fma_f32 v163, s37, v163, v187
	v_fma_f32 v164, s37, v164, v188
	v_fma_f32 v165, s37, v165, v189
	v_fma_f32 v166, s37, v166, v190
	v_fma_f32 v167, s37, v167, v191
	global_store_dwordx4 v203, v[152:155], s[32:33] offset:0
	global_store_dwordx4 v203, v[156:159], s[32:33] offset:64
	global_store_dwordx4 v203, v[160:163], s[32:33] offset:128
	global_store_dwordx4 v203, v[164:167], s[32:33] offset:192
	s_add_u32 s32, s32, 0x20000
	s_addc_u32 s33, s33, 0
	global_load_dwordx4 v[152:155], v203, s[30:31] offset:0
	global_load_dwordx4 v[156:159], v203, s[30:31] offset:64
	global_load_dwordx4 v[160:163], v203, s[30:31] offset:128
	global_load_dwordx4 v[164:167], v203, s[30:31] offset:192
	global_load_dwordx2 v[168:169], v236, s[34:35] offset:0
	global_load_dwordx2 v[170:171], v236, s[34:35] offset:32
	global_load_dwordx2 v[172:173], v236, s[34:35] offset:64
	global_load_dwordx2 v[174:175], v236, s[34:35] offset:96
	s_add_u32 s30, s30, 0x20000
	s_addc_u32 s31, s31, 0
	s_add_u32 s34, s34, 0x1000
	s_addc_u32 s35, s35, 0
	s_waitcnt vmcnt(12)
	v_mul_f32_e32 v176, s36, v96
	v_mul_f32_e32 v177, s36, v97
	v_mul_f32_e32 v178, s36, v98
	v_mul_f32_e32 v179, s36, v99
	v_mul_f32_e32 v180, s36, v100
	v_mul_f32_e32 v181, s36, v101
	v_mul_f32_e32 v182, s36, v102
	v_mul_f32_e32 v183, s36, v103
	v_mul_f32_e32 v184, s36, v104
	v_mul_f32_e32 v185, s36, v105
	v_mul_f32_e32 v186, s36, v106
	v_mul_f32_e32 v187, s36, v107
	v_mul_f32_e32 v188, s36, v108
	v_mul_f32_e32 v189, s36, v109
	v_mul_f32_e32 v190, s36, v110
	v_mul_f32_e32 v191, s36, v111
	v_exp_f32_e32 v176, v176
	v_exp_f32_e32 v177, v177
	v_exp_f32_e32 v178, v178
	v_exp_f32_e32 v179, v179
	v_exp_f32_e32 v180, v180
	v_exp_f32_e32 v181, v181
	v_exp_f32_e32 v182, v182
	v_exp_f32_e32 v183, v183
	v_exp_f32_e32 v184, v184
	v_exp_f32_e32 v185, v185
	v_exp_f32_e32 v186, v186
	v_exp_f32_e32 v187, v187
	v_exp_f32_e32 v188, v188
	v_exp_f32_e32 v189, v189
	v_exp_f32_e32 v190, v190
	v_exp_f32_e32 v191, v191
	v_lshlrev_b32_e32 v96, 16, v144
	v_and_b32_e32 v97, 0xffff0000, v144
	v_lshlrev_b32_e32 v98, 16, v145
	v_and_b32_e32 v99, 0xffff0000, v145
	v_lshlrev_b32_e32 v100, 16, v146
	v_and_b32_e32 v101, 0xffff0000, v146
	v_lshlrev_b32_e32 v102, 16, v147
	v_and_b32_e32 v103, 0xffff0000, v147
	v_lshlrev_b32_e32 v104, 16, v148
	v_and_b32_e32 v105, 0xffff0000, v148
	v_lshlrev_b32_e32 v106, 16, v149
	v_and_b32_e32 v107, 0xffff0000, v149
	v_lshlrev_b32_e32 v108, 16, v150
	v_and_b32_e32 v109, 0xffff0000, v150
	v_lshlrev_b32_e32 v110, 16, v151
	v_and_b32_e32 v111, 0xffff0000, v151
	v_add_f32_e32 v176, 1.0, v176
	v_add_f32_e32 v177, 1.0, v177
	v_add_f32_e32 v178, 1.0, v178
	v_add_f32_e32 v179, 1.0, v179
	v_add_f32_e32 v180, 1.0, v180
	v_add_f32_e32 v181, 1.0, v181
	v_add_f32_e32 v182, 1.0, v182
	v_add_f32_e32 v183, 1.0, v183
	v_add_f32_e32 v184, 1.0, v184
	v_add_f32_e32 v185, 1.0, v185
	v_add_f32_e32 v186, 1.0, v186
	v_add_f32_e32 v187, 1.0, v187
	v_add_f32_e32 v188, 1.0, v188
	v_add_f32_e32 v189, 1.0, v189
	v_add_f32_e32 v190, 1.0, v190
	v_add_f32_e32 v191, 1.0, v191
	v_rcp_f32_e32 v176, v176
	v_rcp_f32_e32 v177, v177
	v_rcp_f32_e32 v178, v178
	v_rcp_f32_e32 v179, v179
	v_rcp_f32_e32 v180, v180
	v_rcp_f32_e32 v181, v181
	v_rcp_f32_e32 v182, v182
	v_rcp_f32_e32 v183, v183
	v_rcp_f32_e32 v184, v184
	v_rcp_f32_e32 v185, v185
	v_rcp_f32_e32 v186, v186
	v_rcp_f32_e32 v187, v187
	v_rcp_f32_e32 v188, v188
	v_rcp_f32_e32 v189, v189
	v_rcp_f32_e32 v190, v190
	v_rcp_f32_e32 v191, v191
	s_nop 0
	v_mul_f32_e32 v176, v176, v96
	v_mul_f32_e32 v177, v177, v97
	v_mul_f32_e32 v178, v178, v98
	v_mul_f32_e32 v179, v179, v99
	v_mul_f32_e32 v180, v180, v100
	v_mul_f32_e32 v181, v181, v101
	v_mul_f32_e32 v182, v182, v102
	v_mul_f32_e32 v183, v183, v103
	v_mul_f32_e32 v184, v184, v104
	v_mul_f32_e32 v185, v185, v105
	v_mul_f32_e32 v186, v186, v106
	v_mul_f32_e32 v187, v187, v107
	v_mul_f32_e32 v188, v188, v108
	v_mul_f32_e32 v189, v189, v109
	v_mul_f32_e32 v190, v190, v110
	v_mul_f32_e32 v191, v191, v111
	v_fma_f32 v128, s37, v128, v176
	v_fma_f32 v129, s37, v129, v177
	v_fma_f32 v130, s37, v130, v178
	v_fma_f32 v131, s37, v131, v179
	v_fma_f32 v132, s37, v132, v180
	v_fma_f32 v133, s37, v133, v181
	v_fma_f32 v134, s37, v134, v182
	v_fma_f32 v135, s37, v135, v183
	v_fma_f32 v136, s37, v136, v184
	v_fma_f32 v137, s37, v137, v185
	v_fma_f32 v138, s37, v138, v186
	v_fma_f32 v139, s37, v139, v187
	v_fma_f32 v140, s37, v140, v188
	v_fma_f32 v141, s37, v141, v189
	v_fma_f32 v142, s37, v142, v190
	v_fma_f32 v143, s37, v143, v191
	global_store_dwordx4 v203, v[128:131], s[32:33] offset:0
	global_store_dwordx4 v203, v[132:135], s[32:33] offset:64
	global_store_dwordx4 v203, v[136:139], s[32:33] offset:128
	global_store_dwordx4 v203, v[140:143], s[32:33] offset:192
	s_add_u32 s32, s32, 0x20000
	s_addc_u32 s33, s33, 0
	s_waitcnt vmcnt(4)
	v_mul_f32_e32 v176, s36, v112
	v_mul_f32_e32 v177, s36, v113
	v_mul_f32_e32 v178, s36, v114
	v_mul_f32_e32 v179, s36, v115
	v_mul_f32_e32 v180, s36, v116
	v_mul_f32_e32 v181, s36, v117
	v_mul_f32_e32 v182, s36, v118
	v_mul_f32_e32 v183, s36, v119
	v_mul_f32_e32 v184, s36, v120
	v_mul_f32_e32 v185, s36, v121
	v_mul_f32_e32 v186, s36, v122
	v_mul_f32_e32 v187, s36, v123
	v_mul_f32_e32 v188, s36, v124
	v_mul_f32_e32 v189, s36, v125
	v_mul_f32_e32 v190, s36, v126
	v_mul_f32_e32 v191, s36, v127
	v_exp_f32_e32 v176, v176
	v_exp_f32_e32 v177, v177
	v_exp_f32_e32 v178, v178
	v_exp_f32_e32 v179, v179
	v_exp_f32_e32 v180, v180
	v_exp_f32_e32 v181, v181
	v_exp_f32_e32 v182, v182
	v_exp_f32_e32 v183, v183
	v_exp_f32_e32 v184, v184
	v_exp_f32_e32 v185, v185
	v_exp_f32_e32 v186, v186
	v_exp_f32_e32 v187, v187
	v_exp_f32_e32 v188, v188
	v_exp_f32_e32 v189, v189
	v_exp_f32_e32 v190, v190
	v_exp_f32_e32 v191, v191
	v_lshlrev_b32_e32 v112, 16, v168
	v_and_b32_e32 v113, 0xffff0000, v168
	v_lshlrev_b32_e32 v114, 16, v169
	v_and_b32_e32 v115, 0xffff0000, v169
	v_lshlrev_b32_e32 v116, 16, v170
	v_and_b32_e32 v117, 0xffff0000, v170
	v_lshlrev_b32_e32 v118, 16, v171
	v_and_b32_e32 v119, 0xffff0000, v171
	v_lshlrev_b32_e32 v120, 16, v172
	v_and_b32_e32 v121, 0xffff0000, v172
	v_lshlrev_b32_e32 v122, 16, v173
	v_and_b32_e32 v123, 0xffff0000, v173
	v_lshlrev_b32_e32 v124, 16, v174
	v_and_b32_e32 v125, 0xffff0000, v174
	v_lshlrev_b32_e32 v126, 16, v175
	v_and_b32_e32 v127, 0xffff0000, v175
	v_add_f32_e32 v176, 1.0, v176
	v_add_f32_e32 v177, 1.0, v177
	v_add_f32_e32 v178, 1.0, v178
	v_add_f32_e32 v179, 1.0, v179
	v_add_f32_e32 v180, 1.0, v180
	v_add_f32_e32 v181, 1.0, v181
	v_add_f32_e32 v182, 1.0, v182
	v_add_f32_e32 v183, 1.0, v183
	v_add_f32_e32 v184, 1.0, v184
	v_add_f32_e32 v185, 1.0, v185
	v_add_f32_e32 v186, 1.0, v186
	v_add_f32_e32 v187, 1.0, v187
	v_add_f32_e32 v188, 1.0, v188
	v_add_f32_e32 v189, 1.0, v189
	v_add_f32_e32 v190, 1.0, v190
	v_add_f32_e32 v191, 1.0, v191
	v_rcp_f32_e32 v176, v176
	v_rcp_f32_e32 v177, v177
	v_rcp_f32_e32 v178, v178
	v_rcp_f32_e32 v179, v179
	v_rcp_f32_e32 v180, v180
	v_rcp_f32_e32 v181, v181
	v_rcp_f32_e32 v182, v182
	v_rcp_f32_e32 v183, v183
	v_rcp_f32_e32 v184, v184
	v_rcp_f32_e32 v185, v185
	v_rcp_f32_e32 v186, v186
	v_rcp_f32_e32 v187, v187
	v_rcp_f32_e32 v188, v188
	v_rcp_f32_e32 v189, v189
	v_rcp_f32_e32 v190, v190
	v_rcp_f32_e32 v191, v191
	s_nop 0
	v_mul_f32_e32 v176, v176, v112
	v_mul_f32_e32 v177, v177, v113
	v_mul_f32_e32 v178, v178, v114
	v_mul_f32_e32 v179, v179, v115
	v_mul_f32_e32 v180, v180, v116
	v_mul_f32_e32 v181, v181, v117
	v_mul_f32_e32 v182, v182, v118
	v_mul_f32_e32 v183, v183, v119
	v_mul_f32_e32 v184, v184, v120
	v_mul_f32_e32 v185, v185, v121
	v_mul_f32_e32 v186, v186, v122
	v_mul_f32_e32 v187, v187, v123
	v_mul_f32_e32 v188, v188, v124
	v_mul_f32_e32 v189, v189, v125
	v_mul_f32_e32 v190, v190, v126
	v_mul_f32_e32 v191, v191, v127
	v_fma_f32 v152, s37, v152, v176
	v_fma_f32 v153, s37, v153, v177
	v_fma_f32 v154, s37, v154, v178
	v_fma_f32 v155, s37, v155, v179
	v_fma_f32 v156, s37, v156, v180
	v_fma_f32 v157, s37, v157, v181
	v_fma_f32 v158, s37, v158, v182
	v_fma_f32 v159, s37, v159, v183
	v_fma_f32 v160, s37, v160, v184
	v_fma_f32 v161, s37, v161, v185
	v_fma_f32 v162, s37, v162, v186
	v_fma_f32 v163, s37, v163, v187
	v_fma_f32 v164, s37, v164, v188
	v_fma_f32 v165, s37, v165, v189
	v_fma_f32 v166, s37, v166, v190
	v_fma_f32 v167, s37, v167, v191
	global_store_dwordx4 v203, v[152:155], s[32:33] offset:0
	global_store_dwordx4 v203, v[156:159], s[32:33] offset:64
	global_store_dwordx4 v203, v[160:163], s[32:33] offset:128
	global_store_dwordx4 v203, v[164:167], s[32:33] offset:192
	s_add_u32 s32, s32, 0x20000
	s_addc_u32 s33, s33, 0
	s_sub_u32 s34, s34, 0x8000
	s_subb_u32 s35, s35, 0
	s_add_u32 s29, s29, 0x200
	s_cmp_lt_u32 s29, 0x400
	s_cbranch_scc1 .Lple_tile
	s_waitcnt vmcnt(0)
	s_branch .LBB0_980
